# adds: adaLN GEMV 16-deep double-buffered loads; retention core LDS fragment reads pipelined through unused registers; retention waves renumbered for SIMD balance
# speedup vs baseline: 1.0172x; 1.0138x over previous
.LBB0_119:
	s_mov_b64 s[0:1], 0x9000
	v_mov_b32_e32 v76, v14
	v_mov_b32_e32 v77, v15
	global_load_dword v104, v[76:77], off nt
	v_lshl_add_u64 v[76:77], v[76:77], 0, s[0:1]
	global_load_dword v105, v[76:77], off nt
	v_lshl_add_u64 v[76:77], v[76:77], 0, s[0:1]
	global_load_dword v106, v[76:77], off nt
	v_lshl_add_u64 v[76:77], v[76:77], 0, s[0:1]
	global_load_dword v107, v[76:77], off nt
	v_lshl_add_u64 v[76:77], v[76:77], 0, s[0:1]
	global_load_dword v108, v[76:77], off nt
	v_lshl_add_u64 v[76:77], v[76:77], 0, s[0:1]
	global_load_dword v109, v[76:77], off nt
	v_lshl_add_u64 v[76:77], v[76:77], 0, s[0:1]
	global_load_dword v110, v[76:77], off nt
	v_lshl_add_u64 v[76:77], v[76:77], 0, s[0:1]
	global_load_dword v111, v[76:77], off nt
	v_lshl_add_u64 v[76:77], v[76:77], 0, s[0:1]
	global_load_dword v112, v[76:77], off nt
	v_lshl_add_u64 v[76:77], v[76:77], 0, s[0:1]
	global_load_dword v113, v[76:77], off nt
	v_lshl_add_u64 v[76:77], v[76:77], 0, s[0:1]
	global_load_dword v114, v[76:77], off nt
	v_lshl_add_u64 v[76:77], v[76:77], 0, s[0:1]
	global_load_dword v115, v[76:77], off nt
	v_lshl_add_u64 v[76:77], v[76:77], 0, s[0:1]
	global_load_dword v116, v[76:77], off nt
	v_lshl_add_u64 v[76:77], v[76:77], 0, s[0:1]
	global_load_dword v117, v[76:77], off nt
	v_lshl_add_u64 v[76:77], v[76:77], 0, s[0:1]
	global_load_dword v118, v[76:77], off nt
	v_lshl_add_u64 v[76:77], v[76:77], 0, s[0:1]
	global_load_dword v119, v[76:77], off nt
	v_lshl_add_u64 v[76:77], v[76:77], 0, s[0:1]
	s_mov_b32 s42, 7
.Lada_loop:
	global_load_dword v140, v[76:77], off nt
	v_lshl_add_u64 v[76:77], v[76:77], 0, s[0:1]
	global_load_dword v141, v[76:77], off nt
	v_lshl_add_u64 v[76:77], v[76:77], 0, s[0:1]
	global_load_dword v142, v[76:77], off nt
	v_lshl_add_u64 v[76:77], v[76:77], 0, s[0:1]
	global_load_dword v143, v[76:77], off nt
	v_lshl_add_u64 v[76:77], v[76:77], 0, s[0:1]
	global_load_dword v144, v[76:77], off nt
	v_lshl_add_u64 v[76:77], v[76:77], 0, s[0:1]
	global_load_dword v145, v[76:77], off nt
	v_lshl_add_u64 v[76:77], v[76:77], 0, s[0:1]
	global_load_dword v146, v[76:77], off nt
	v_lshl_add_u64 v[76:77], v[76:77], 0, s[0:1]
	global_load_dword v147, v[76:77], off nt
	v_lshl_add_u64 v[76:77], v[76:77], 0, s[0:1]
	global_load_dword v148, v[76:77], off nt
	v_lshl_add_u64 v[76:77], v[76:77], 0, s[0:1]
	global_load_dword v149, v[76:77], off nt
	v_lshl_add_u64 v[76:77], v[76:77], 0, s[0:1]
	global_load_dword v150, v[76:77], off nt
	v_lshl_add_u64 v[76:77], v[76:77], 0, s[0:1]
	global_load_dword v151, v[76:77], off nt
	v_lshl_add_u64 v[76:77], v[76:77], 0, s[0:1]
	global_load_dword v152, v[76:77], off nt
	v_lshl_add_u64 v[76:77], v[76:77], 0, s[0:1]
	global_load_dword v153, v[76:77], off nt
	v_lshl_add_u64 v[76:77], v[76:77], 0, s[0:1]
	global_load_dword v154, v[76:77], off nt
	v_lshl_add_u64 v[76:77], v[76:77], 0, s[0:1]
	global_load_dword v155, v[76:77], off nt
	v_lshl_add_u64 v[76:77], v[76:77], 0, s[0:1]
	s_waitcnt vmcnt(16)
	ds_read_b128 v[44:47], v32 offset:0
	ds_read_b128 v[48:51], v32 offset:16
	ds_read_b128 v[52:55], v32 offset:32
	ds_read_b128 v[56:59], v32 offset:48
	ds_read_b128 v[60:63], v32 offset:64
	ds_read_b128 v[64:67], v32 offset:80
	ds_read_b128 v[68:71], v32 offset:96
	ds_read_b128 v[72:75], v32 offset:112
	s_waitcnt lgkmcnt(4)
	v_pk_fma_f32 v[28:29], v[44:45], v[104:105], v[28:29] op_sel_hi:[1,0,1]
	v_pk_fma_f32 v[30:31], v[46:47], v[104:105], v[30:31] op_sel_hi:[1,0,1]
	v_pk_fma_f32 v[26:27], v[48:49], v[104:105], v[26:27] op_sel_hi:[1,0,1]
	v_pk_fma_f32 v[24:25], v[50:51], v[104:105], v[24:25] op_sel_hi:[1,0,1]
	v_pk_fma_f32 v[22:23], v[52:53], v[104:105], v[22:23] op_sel_hi:[1,0,1]
	v_pk_fma_f32 v[20:21], v[54:55], v[104:105], v[20:21] op_sel_hi:[1,0,1]
	v_pk_fma_f32 v[18:19], v[56:57], v[104:105], v[18:19] op_sel_hi:[1,0,1]
	v_pk_fma_f32 v[16:17], v[58:59], v[104:105], v[16:17] op_sel_hi:[1,0,1]
	ds_read_b128 v[44:47], v32 offset:128
	ds_read_b128 v[48:51], v32 offset:144
	ds_read_b128 v[52:55], v32 offset:160
	ds_read_b128 v[56:59], v32 offset:176
	s_waitcnt lgkmcnt(4)
	v_pk_fma_f32 v[28:29], v[60:61], v[104:105], v[28:29] op_sel:[0,1,0] op_sel_hi:[1,1,1]
	v_pk_fma_f32 v[30:31], v[62:63], v[104:105], v[30:31] op_sel:[0,1,0] op_sel_hi:[1,1,1]
	v_pk_fma_f32 v[26:27], v[64:65], v[104:105], v[26:27] op_sel:[0,1,0] op_sel_hi:[1,1,1]
	v_pk_fma_f32 v[24:25], v[66:67], v[104:105], v[24:25] op_sel:[0,1,0] op_sel_hi:[1,1,1]
	v_pk_fma_f32 v[22:23], v[68:69], v[104:105], v[22:23] op_sel:[0,1,0] op_sel_hi:[1,1,1]
	v_pk_fma_f32 v[20:21], v[70:71], v[104:105], v[20:21] op_sel:[0,1,0] op_sel_hi:[1,1,1]
	v_pk_fma_f32 v[18:19], v[72:73], v[104:105], v[18:19] op_sel:[0,1,0] op_sel_hi:[1,1,1]
	v_pk_fma_f32 v[16:17], v[74:75], v[104:105], v[16:17] op_sel:[0,1,0] op_sel_hi:[1,1,1]
	ds_read_b128 v[60:63], v32 offset:192
	ds_read_b128 v[64:67], v32 offset:208
	ds_read_b128 v[68:71], v32 offset:224
	ds_read_b128 v[72:75], v32 offset:240
	s_waitcnt lgkmcnt(4)
	v_pk_fma_f32 v[28:29], v[44:45], v[106:107], v[28:29] op_sel_hi:[1,0,1]
	v_pk_fma_f32 v[30:31], v[46:47], v[106:107], v[30:31] op_sel_hi:[1,0,1]
	v_pk_fma_f32 v[26:27], v[48:49], v[106:107], v[26:27] op_sel_hi:[1,0,1]
	v_pk_fma_f32 v[24:25], v[50:51], v[106:107], v[24:25] op_sel_hi:[1,0,1]
	v_pk_fma_f32 v[22:23], v[52:53], v[106:107], v[22:23] op_sel_hi:[1,0,1]
	v_pk_fma_f32 v[20:21], v[54:55], v[106:107], v[20:21] op_sel_hi:[1,0,1]
	v_pk_fma_f32 v[18:19], v[56:57], v[106:107], v[18:19] op_sel_hi:[1,0,1]
	v_pk_fma_f32 v[16:17], v[58:59], v[106:107], v[16:17] op_sel_hi:[1,0,1]
	ds_read_b128 v[44:47], v32 offset:256
	ds_read_b128 v[48:51], v32 offset:272
	ds_read_b128 v[52:55], v32 offset:288
	ds_read_b128 v[56:59], v32 offset:304
	s_waitcnt lgkmcnt(4)
	v_pk_fma_f32 v[28:29], v[60:61], v[106:107], v[28:29] op_sel:[0,1,0] op_sel_hi:[1,1,1]
	v_pk_fma_f32 v[30:31], v[62:63], v[106:107], v[30:31] op_sel:[0,1,0] op_sel_hi:[1,1,1]
	v_pk_fma_f32 v[26:27], v[64:65], v[106:107], v[26:27] op_sel:[0,1,0] op_sel_hi:[1,1,1]
	v_pk_fma_f32 v[24:25], v[66:67], v[106:107], v[24:25] op_sel:[0,1,0] op_sel_hi:[1,1,1]
	v_pk_fma_f32 v[22:23], v[68:69], v[106:107], v[22:23] op_sel:[0,1,0] op_sel_hi:[1,1,1]
	v_pk_fma_f32 v[20:21], v[70:71], v[106:107], v[20:21] op_sel:[0,1,0] op_sel_hi:[1,1,1]
	v_pk_fma_f32 v[18:19], v[72:73], v[106:107], v[18:19] op_sel:[0,1,0] op_sel_hi:[1,1,1]
	v_pk_fma_f32 v[16:17], v[74:75], v[106:107], v[16:17] op_sel:[0,1,0] op_sel_hi:[1,1,1]
	ds_read_b128 v[60:63], v32 offset:320
	ds_read_b128 v[64:67], v32 offset:336
	ds_read_b128 v[68:71], v32 offset:352
	ds_read_b128 v[72:75], v32 offset:368
	s_waitcnt lgkmcnt(4)
	v_pk_fma_f32 v[28:29], v[44:45], v[108:109], v[28:29] op_sel_hi:[1,0,1]
	v_pk_fma_f32 v[30:31], v[46:47], v[108:109], v[30:31] op_sel_hi:[1,0,1]
	v_pk_fma_f32 v[26:27], v[48:49], v[108:109], v[26:27] op_sel_hi:[1,0,1]
	v_pk_fma_f32 v[24:25], v[50:51], v[108:109], v[24:25] op_sel_hi:[1,0,1]
	v_pk_fma_f32 v[22:23], v[52:53], v[108:109], v[22:23] op_sel_hi:[1,0,1]
	v_pk_fma_f32 v[20:21], v[54:55], v[108:109], v[20:21] op_sel_hi:[1,0,1]
	v_pk_fma_f32 v[18:19], v[56:57], v[108:109], v[18:19] op_sel_hi:[1,0,1]
	v_pk_fma_f32 v[16:17], v[58:59], v[108:109], v[16:17] op_sel_hi:[1,0,1]
	ds_read_b128 v[44:47], v32 offset:384
	ds_read_b128 v[48:51], v32 offset:400
	ds_read_b128 v[52:55], v32 offset:416
	ds_read_b128 v[56:59], v32 offset:432
	s_waitcnt lgkmcnt(4)
	v_pk_fma_f32 v[28:29], v[60:61], v[108:109], v[28:29] op_sel:[0,1,0] op_sel_hi:[1,1,1]
	v_pk_fma_f32 v[30:31], v[62:63], v[108:109], v[30:31] op_sel:[0,1,0] op_sel_hi:[1,1,1]
	v_pk_fma_f32 v[26:27], v[64:65], v[108:109], v[26:27] op_sel:[0,1,0] op_sel_hi:[1,1,1]
	v_pk_fma_f32 v[24:25], v[66:67], v[108:109], v[24:25] op_sel:[0,1,0] op_sel_hi:[1,1,1]
	v_pk_fma_f32 v[22:23], v[68:69], v[108:109], v[22:23] op_sel:[0,1,0] op_sel_hi:[1,1,1]
	v_pk_fma_f32 v[20:21], v[70:71], v[108:109], v[20:21] op_sel:[0,1,0] op_sel_hi:[1,1,1]
	v_pk_fma_f32 v[18:19], v[72:73], v[108:109], v[18:19] op_sel:[0,1,0] op_sel_hi:[1,1,1]
	v_pk_fma_f32 v[16:17], v[74:75], v[108:109], v[16:17] op_sel:[0,1,0] op_sel_hi:[1,1,1]
	ds_read_b128 v[60:63], v32 offset:448
	ds_read_b128 v[64:67], v32 offset:464
	ds_read_b128 v[68:71], v32 offset:480
	ds_read_b128 v[72:75], v32 offset:496
	s_waitcnt lgkmcnt(4)
	v_pk_fma_f32 v[28:29], v[44:45], v[110:111], v[28:29] op_sel_hi:[1,0,1]
	v_pk_fma_f32 v[30:31], v[46:47], v[110:111], v[30:31] op_sel_hi:[1,0,1]
	v_pk_fma_f32 v[26:27], v[48:49], v[110:111], v[26:27] op_sel_hi:[1,0,1]
	v_pk_fma_f32 v[24:25], v[50:51], v[110:111], v[24:25] op_sel_hi:[1,0,1]
	v_pk_fma_f32 v[22:23], v[52:53], v[110:111], v[22:23] op_sel_hi:[1,0,1]
	v_pk_fma_f32 v[20:21], v[54:55], v[110:111], v[20:21] op_sel_hi:[1,0,1]
	v_pk_fma_f32 v[18:19], v[56:57], v[110:111], v[18:19] op_sel_hi:[1,0,1]
	v_pk_fma_f32 v[16:17], v[58:59], v[110:111], v[16:17] op_sel_hi:[1,0,1]
	ds_read_b128 v[44:47], v32 offset:512
	ds_read_b128 v[48:51], v32 offset:528
	ds_read_b128 v[52:55], v32 offset:544
	ds_read_b128 v[56:59], v32 offset:560
	s_waitcnt lgkmcnt(4)
	v_pk_fma_f32 v[28:29], v[60:61], v[110:111], v[28:29] op_sel:[0,1,0] op_sel_hi:[1,1,1]
	v_pk_fma_f32 v[30:31], v[62:63], v[110:111], v[30:31] op_sel:[0,1,0] op_sel_hi:[1,1,1]
	v_pk_fma_f32 v[26:27], v[64:65], v[110:111], v[26:27] op_sel:[0,1,0] op_sel_hi:[1,1,1]
	v_pk_fma_f32 v[24:25], v[66:67], v[110:111], v[24:25] op_sel:[0,1,0] op_sel_hi:[1,1,1]
	v_pk_fma_f32 v[22:23], v[68:69], v[110:111], v[22:23] op_sel:[0,1,0] op_sel_hi:[1,1,1]
	v_pk_fma_f32 v[20:21], v[70:71], v[110:111], v[20:21] op_sel:[0,1,0] op_sel_hi:[1,1,1]
	v_pk_fma_f32 v[18:19], v[72:73], v[110:111], v[18:19] op_sel:[0,1,0] op_sel_hi:[1,1,1]
	v_pk_fma_f32 v[16:17], v[74:75], v[110:111], v[16:17] op_sel:[0,1,0] op_sel_hi:[1,1,1]
	ds_read_b128 v[60:63], v32 offset:576
	ds_read_b128 v[64:67], v32 offset:592
	ds_read_b128 v[68:71], v32 offset:608
	ds_read_b128 v[72:75], v32 offset:624
	s_waitcnt lgkmcnt(4)
	v_pk_fma_f32 v[28:29], v[44:45], v[112:113], v[28:29] op_sel_hi:[1,0,1]
	v_pk_fma_f32 v[30:31], v[46:47], v[112:113], v[30:31] op_sel_hi:[1,0,1]
	v_pk_fma_f32 v[26:27], v[48:49], v[112:113], v[26:27] op_sel_hi:[1,0,1]
	v_pk_fma_f32 v[24:25], v[50:51], v[112:113], v[24:25] op_sel_hi:[1,0,1]
	v_pk_fma_f32 v[22:23], v[52:53], v[112:113], v[22:23] op_sel_hi:[1,0,1]
	v_pk_fma_f32 v[20:21], v[54:55], v[112:113], v[20:21] op_sel_hi:[1,0,1]
	v_pk_fma_f32 v[18:19], v[56:57], v[112:113], v[18:19] op_sel_hi:[1,0,1]
	v_pk_fma_f32 v[16:17], v[58:59], v[112:113], v[16:17] op_sel_hi:[1,0,1]
	ds_read_b128 v[44:47], v32 offset:640
	ds_read_b128 v[48:51], v32 offset:656
	ds_read_b128 v[52:55], v32 offset:672
	ds_read_b128 v[56:59], v32 offset:688
	s_waitcnt lgkmcnt(4)
	v_pk_fma_f32 v[28:29], v[60:61], v[112:113], v[28:29] op_sel:[0,1,0] op_sel_hi:[1,1,1]
	v_pk_fma_f32 v[30:31], v[62:63], v[112:113], v[30:31] op_sel:[0,1,0] op_sel_hi:[1,1,1]
	v_pk_fma_f32 v[26:27], v[64:65], v[112:113], v[26:27] op_sel:[0,1,0] op_sel_hi:[1,1,1]
	v_pk_fma_f32 v[24:25], v[66:67], v[112:113], v[24:25] op_sel:[0,1,0] op_sel_hi:[1,1,1]
	v_pk_fma_f32 v[22:23], v[68:69], v[112:113], v[22:23] op_sel:[0,1,0] op_sel_hi:[1,1,1]
	v_pk_fma_f32 v[20:21], v[70:71], v[112:113], v[20:21] op_sel:[0,1,0] op_sel_hi:[1,1,1]
	v_pk_fma_f32 v[18:19], v[72:73], v[112:113], v[18:19] op_sel:[0,1,0] op_sel_hi:[1,1,1]
	v_pk_fma_f32 v[16:17], v[74:75], v[112:113], v[16:17] op_sel:[0,1,0] op_sel_hi:[1,1,1]
	ds_read_b128 v[60:63], v32 offset:704
	ds_read_b128 v[64:67], v32 offset:720
	ds_read_b128 v[68:71], v32 offset:736
	ds_read_b128 v[72:75], v32 offset:752
	s_waitcnt lgkmcnt(4)
	v_pk_fma_f32 v[28:29], v[44:45], v[114:115], v[28:29] op_sel_hi:[1,0,1]
	v_pk_fma_f32 v[30:31], v[46:47], v[114:115], v[30:31] op_sel_hi:[1,0,1]
	v_pk_fma_f32 v[26:27], v[48:49], v[114:115], v[26:27] op_sel_hi:[1,0,1]
	v_pk_fma_f32 v[24:25], v[50:51], v[114:115], v[24:25] op_sel_hi:[1,0,1]
	v_pk_fma_f32 v[22:23], v[52:53], v[114:115], v[22:23] op_sel_hi:[1,0,1]
	v_pk_fma_f32 v[20:21], v[54:55], v[114:115], v[20:21] op_sel_hi:[1,0,1]
	v_pk_fma_f32 v[18:19], v[56:57], v[114:115], v[18:19] op_sel_hi:[1,0,1]
	v_pk_fma_f32 v[16:17], v[58:59], v[114:115], v[16:17] op_sel_hi:[1,0,1]
	ds_read_b128 v[44:47], v32 offset:768
	ds_read_b128 v[48:51], v32 offset:784
	ds_read_b128 v[52:55], v32 offset:800
	ds_read_b128 v[56:59], v32 offset:816
	s_waitcnt lgkmcnt(4)
	v_pk_fma_f32 v[28:29], v[60:61], v[114:115], v[28:29] op_sel:[0,1,0] op_sel_hi:[1,1,1]
	v_pk_fma_f32 v[30:31], v[62:63], v[114:115], v[30:31] op_sel:[0,1,0] op_sel_hi:[1,1,1]
	v_pk_fma_f32 v[26:27], v[64:65], v[114:115], v[26:27] op_sel:[0,1,0] op_sel_hi:[1,1,1]
	v_pk_fma_f32 v[24:25], v[66:67], v[114:115], v[24:25] op_sel:[0,1,0] op_sel_hi:[1,1,1]
	v_pk_fma_f32 v[22:23], v[68:69], v[114:115], v[22:23] op_sel:[0,1,0] op_sel_hi:[1,1,1]
	v_pk_fma_f32 v[20:21], v[70:71], v[114:115], v[20:21] op_sel:[0,1,0] op_sel_hi:[1,1,1]
	v_pk_fma_f32 v[18:19], v[72:73], v[114:115], v[18:19] op_sel:[0,1,0] op_sel_hi:[1,1,1]
	v_pk_fma_f32 v[16:17], v[74:75], v[114:115], v[16:17] op_sel:[0,1,0] op_sel_hi:[1,1,1]
	ds_read_b128 v[60:63], v32 offset:832
	ds_read_b128 v[64:67], v32 offset:848
	ds_read_b128 v[68:71], v32 offset:864
	ds_read_b128 v[72:75], v32 offset:880
	s_waitcnt lgkmcnt(4)
	v_pk_fma_f32 v[28:29], v[44:45], v[116:117], v[28:29] op_sel_hi:[1,0,1]
	v_pk_fma_f32 v[30:31], v[46:47], v[116:117], v[30:31] op_sel_hi:[1,0,1]
	v_pk_fma_f32 v[26:27], v[48:49], v[116:117], v[26:27] op_sel_hi:[1,0,1]
	v_pk_fma_f32 v[24:25], v[50:51], v[116:117], v[24:25] op_sel_hi:[1,0,1]
	v_pk_fma_f32 v[22:23], v[52:53], v[116:117], v[22:23] op_sel_hi:[1,0,1]
	v_pk_fma_f32 v[20:21], v[54:55], v[116:117], v[20:21] op_sel_hi:[1,0,1]
	v_pk_fma_f32 v[18:19], v[56:57], v[116:117], v[18:19] op_sel_hi:[1,0,1]
	v_pk_fma_f32 v[16:17], v[58:59], v[116:117], v[16:17] op_sel_hi:[1,0,1]
	ds_read_b128 v[44:47], v32 offset:896
	ds_read_b128 v[48:51], v32 offset:912
	ds_read_b128 v[52:55], v32 offset:928
	ds_read_b128 v[56:59], v32 offset:944
	s_waitcnt lgkmcnt(4)
	v_pk_fma_f32 v[28:29], v[60:61], v[116:117], v[28:29] op_sel:[0,1,0] op_sel_hi:[1,1,1]
	v_pk_fma_f32 v[30:31], v[62:63], v[116:117], v[30:31] op_sel:[0,1,0] op_sel_hi:[1,1,1]
	v_pk_fma_f32 v[26:27], v[64:65], v[116:117], v[26:27] op_sel:[0,1,0] op_sel_hi:[1,1,1]
	v_pk_fma_f32 v[24:25], v[66:67], v[116:117], v[24:25] op_sel:[0,1,0] op_sel_hi:[1,1,1]
	v_pk_fma_f32 v[22:23], v[68:69], v[116:117], v[22:23] op_sel:[0,1,0] op_sel_hi:[1,1,1]
	v_pk_fma_f32 v[20:21], v[70:71], v[116:117], v[20:21] op_sel:[0,1,0] op_sel_hi:[1,1,1]
	v_pk_fma_f32 v[18:19], v[72:73], v[116:117], v[18:19] op_sel:[0,1,0] op_sel_hi:[1,1,1]
	v_pk_fma_f32 v[16:17], v[74:75], v[116:117], v[16:17] op_sel:[0,1,0] op_sel_hi:[1,1,1]
	ds_read_b128 v[60:63], v32 offset:960
	ds_read_b128 v[64:67], v32 offset:976
	ds_read_b128 v[68:71], v32 offset:992
	ds_read_b128 v[72:75], v32 offset:1008
	s_waitcnt lgkmcnt(4)
	v_pk_fma_f32 v[28:29], v[44:45], v[118:119], v[28:29] op_sel_hi:[1,0,1]
	v_pk_fma_f32 v[30:31], v[46:47], v[118:119], v[30:31] op_sel_hi:[1,0,1]
	v_pk_fma_f32 v[26:27], v[48:49], v[118:119], v[26:27] op_sel_hi:[1,0,1]
	v_pk_fma_f32 v[24:25], v[50:51], v[118:119], v[24:25] op_sel_hi:[1,0,1]
	v_pk_fma_f32 v[22:23], v[52:53], v[118:119], v[22:23] op_sel_hi:[1,0,1]
	v_pk_fma_f32 v[20:21], v[54:55], v[118:119], v[20:21] op_sel_hi:[1,0,1]
	v_pk_fma_f32 v[18:19], v[56:57], v[118:119], v[18:19] op_sel_hi:[1,0,1]
	v_pk_fma_f32 v[16:17], v[58:59], v[118:119], v[16:17] op_sel_hi:[1,0,1]
	s_waitcnt lgkmcnt(0)
	v_pk_fma_f32 v[28:29], v[60:61], v[118:119], v[28:29] op_sel:[0,1,0] op_sel_hi:[1,1,1]
	v_pk_fma_f32 v[30:31], v[62:63], v[118:119], v[30:31] op_sel:[0,1,0] op_sel_hi:[1,1,1]
	v_pk_fma_f32 v[26:27], v[64:65], v[118:119], v[26:27] op_sel:[0,1,0] op_sel_hi:[1,1,1]
	v_pk_fma_f32 v[24:25], v[66:67], v[118:119], v[24:25] op_sel:[0,1,0] op_sel_hi:[1,1,1]
	v_pk_fma_f32 v[22:23], v[68:69], v[118:119], v[22:23] op_sel:[0,1,0] op_sel_hi:[1,1,1]
	v_pk_fma_f32 v[20:21], v[70:71], v[118:119], v[20:21] op_sel:[0,1,0] op_sel_hi:[1,1,1]
	v_pk_fma_f32 v[18:19], v[72:73], v[118:119], v[18:19] op_sel:[0,1,0] op_sel_hi:[1,1,1]
	v_pk_fma_f32 v[16:17], v[74:75], v[118:119], v[16:17] op_sel:[0,1,0] op_sel_hi:[1,1,1]
	v_add_u32_e32 v32, 0x400, v32
	global_load_dword v104, v[76:77], off nt
	v_lshl_add_u64 v[76:77], v[76:77], 0, s[0:1]
	global_load_dword v105, v[76:77], off nt
	v_lshl_add_u64 v[76:77], v[76:77], 0, s[0:1]
	global_load_dword v106, v[76:77], off nt
	v_lshl_add_u64 v[76:77], v[76:77], 0, s[0:1]
	global_load_dword v107, v[76:77], off nt
	v_lshl_add_u64 v[76:77], v[76:77], 0, s[0:1]
	global_load_dword v108, v[76:77], off nt
	v_lshl_add_u64 v[76:77], v[76:77], 0, s[0:1]
	global_load_dword v109, v[76:77], off nt
	v_lshl_add_u64 v[76:77], v[76:77], 0, s[0:1]
	global_load_dword v110, v[76:77], off nt
	v_lshl_add_u64 v[76:77], v[76:77], 0, s[0:1]
	global_load_dword v111, v[76:77], off nt
	v_lshl_add_u64 v[76:77], v[76:77], 0, s[0:1]
	global_load_dword v112, v[76:77], off nt
	v_lshl_add_u64 v[76:77], v[76:77], 0, s[0:1]
	global_load_dword v113, v[76:77], off nt
	v_lshl_add_u64 v[76:77], v[76:77], 0, s[0:1]
	global_load_dword v114, v[76:77], off nt
	v_lshl_add_u64 v[76:77], v[76:77], 0, s[0:1]
	global_load_dword v115, v[76:77], off nt
	v_lshl_add_u64 v[76:77], v[76:77], 0, s[0:1]
	global_load_dword v116, v[76:77], off nt
	v_lshl_add_u64 v[76:77], v[76:77], 0, s[0:1]
	global_load_dword v117, v[76:77], off nt
	v_lshl_add_u64 v[76:77], v[76:77], 0, s[0:1]
	global_load_dword v118, v[76:77], off nt
	v_lshl_add_u64 v[76:77], v[76:77], 0, s[0:1]
	global_load_dword v119, v[76:77], off nt
	v_lshl_add_u64 v[76:77], v[76:77], 0, s[0:1]
	s_waitcnt vmcnt(16)
	ds_read_b128 v[44:47], v32 offset:0
	ds_read_b128 v[48:51], v32 offset:16
	ds_read_b128 v[52:55], v32 offset:32
	ds_read_b128 v[56:59], v32 offset:48
	ds_read_b128 v[60:63], v32 offset:64
	ds_read_b128 v[64:67], v32 offset:80
	ds_read_b128 v[68:71], v32 offset:96
	ds_read_b128 v[72:75], v32 offset:112
	s_waitcnt lgkmcnt(4)
	v_pk_fma_f32 v[28:29], v[44:45], v[140:141], v[28:29] op_sel_hi:[1,0,1]
	v_pk_fma_f32 v[30:31], v[46:47], v[140:141], v[30:31] op_sel_hi:[1,0,1]
	v_pk_fma_f32 v[26:27], v[48:49], v[140:141], v[26:27] op_sel_hi:[1,0,1]
	v_pk_fma_f32 v[24:25], v[50:51], v[140:141], v[24:25] op_sel_hi:[1,0,1]
	v_pk_fma_f32 v[22:23], v[52:53], v[140:141], v[22:23] op_sel_hi:[1,0,1]
	v_pk_fma_f32 v[20:21], v[54:55], v[140:141], v[20:21] op_sel_hi:[1,0,1]
	v_pk_fma_f32 v[18:19], v[56:57], v[140:141], v[18:19] op_sel_hi:[1,0,1]
	v_pk_fma_f32 v[16:17], v[58:59], v[140:141], v[16:17] op_sel_hi:[1,0,1]
	ds_read_b128 v[44:47], v32 offset:128
	ds_read_b128 v[48:51], v32 offset:144
	ds_read_b128 v[52:55], v32 offset:160
	ds_read_b128 v[56:59], v32 offset:176
	s_waitcnt lgkmcnt(4)
	v_pk_fma_f32 v[28:29], v[60:61], v[140:141], v[28:29] op_sel:[0,1,0] op_sel_hi:[1,1,1]
	v_pk_fma_f32 v[30:31], v[62:63], v[140:141], v[30:31] op_sel:[0,1,0] op_sel_hi:[1,1,1]
	v_pk_fma_f32 v[26:27], v[64:65], v[140:141], v[26:27] op_sel:[0,1,0] op_sel_hi:[1,1,1]
	v_pk_fma_f32 v[24:25], v[66:67], v[140:141], v[24:25] op_sel:[0,1,0] op_sel_hi:[1,1,1]
	v_pk_fma_f32 v[22:23], v[68:69], v[140:141], v[22:23] op_sel:[0,1,0] op_sel_hi:[1,1,1]
	v_pk_fma_f32 v[20:21], v[70:71], v[140:141], v[20:21] op_sel:[0,1,0] op_sel_hi:[1,1,1]
	v_pk_fma_f32 v[18:19], v[72:73], v[140:141], v[18:19] op_sel:[0,1,0] op_sel_hi:[1,1,1]
	v_pk_fma_f32 v[16:17], v[74:75], v[140:141], v[16:17] op_sel:[0,1,0] op_sel_hi:[1,1,1]
	ds_read_b128 v[60:63], v32 offset:192
	ds_read_b128 v[64:67], v32 offset:208
	ds_read_b128 v[68:71], v32 offset:224
	ds_read_b128 v[72:75], v32 offset:240
	s_waitcnt lgkmcnt(4)
	v_pk_fma_f32 v[28:29], v[44:45], v[142:143], v[28:29] op_sel_hi:[1,0,1]
	v_pk_fma_f32 v[30:31], v[46:47], v[142:143], v[30:31] op_sel_hi:[1,0,1]
	v_pk_fma_f32 v[26:27], v[48:49], v[142:143], v[26:27] op_sel_hi:[1,0,1]
	v_pk_fma_f32 v[24:25], v[50:51], v[142:143], v[24:25] op_sel_hi:[1,0,1]
	v_pk_fma_f32 v[22:23], v[52:53], v[142:143], v[22:23] op_sel_hi:[1,0,1]
	v_pk_fma_f32 v[20:21], v[54:55], v[142:143], v[20:21] op_sel_hi:[1,0,1]
	v_pk_fma_f32 v[18:19], v[56:57], v[142:143], v[18:19] op_sel_hi:[1,0,1]
	v_pk_fma_f32 v[16:17], v[58:59], v[142:143], v[16:17] op_sel_hi:[1,0,1]
	ds_read_b128 v[44:47], v32 offset:256
	ds_read_b128 v[48:51], v32 offset:272
	ds_read_b128 v[52:55], v32 offset:288
	ds_read_b128 v[56:59], v32 offset:304
	s_waitcnt lgkmcnt(4)
	v_pk_fma_f32 v[28:29], v[60:61], v[142:143], v[28:29] op_sel:[0,1,0] op_sel_hi:[1,1,1]
	v_pk_fma_f32 v[30:31], v[62:63], v[142:143], v[30:31] op_sel:[0,1,0] op_sel_hi:[1,1,1]
	v_pk_fma_f32 v[26:27], v[64:65], v[142:143], v[26:27] op_sel:[0,1,0] op_sel_hi:[1,1,1]
	v_pk_fma_f32 v[24:25], v[66:67], v[142:143], v[24:25] op_sel:[0,1,0] op_sel_hi:[1,1,1]
	v_pk_fma_f32 v[22:23], v[68:69], v[142:143], v[22:23] op_sel:[0,1,0] op_sel_hi:[1,1,1]
	v_pk_fma_f32 v[20:21], v[70:71], v[142:143], v[20:21] op_sel:[0,1,0] op_sel_hi:[1,1,1]
	v_pk_fma_f32 v[18:19], v[72:73], v[142:143], v[18:19] op_sel:[0,1,0] op_sel_hi:[1,1,1]
	v_pk_fma_f32 v[16:17], v[74:75], v[142:143], v[16:17] op_sel:[0,1,0] op_sel_hi:[1,1,1]
	ds_read_b128 v[60:63], v32 offset:320
	ds_read_b128 v[64:67], v32 offset:336
	ds_read_b128 v[68:71], v32 offset:352
	ds_read_b128 v[72:75], v32 offset:368
	s_waitcnt lgkmcnt(4)
	v_pk_fma_f32 v[28:29], v[44:45], v[144:145], v[28:29] op_sel_hi:[1,0,1]
	v_pk_fma_f32 v[30:31], v[46:47], v[144:145], v[30:31] op_sel_hi:[1,0,1]
	v_pk_fma_f32 v[26:27], v[48:49], v[144:145], v[26:27] op_sel_hi:[1,0,1]
	v_pk_fma_f32 v[24:25], v[50:51], v[144:145], v[24:25] op_sel_hi:[1,0,1]
	v_pk_fma_f32 v[22:23], v[52:53], v[144:145], v[22:23] op_sel_hi:[1,0,1]
	v_pk_fma_f32 v[20:21], v[54:55], v[144:145], v[20:21] op_sel_hi:[1,0,1]
	v_pk_fma_f32 v[18:19], v[56:57], v[144:145], v[18:19] op_sel_hi:[1,0,1]
	v_pk_fma_f32 v[16:17], v[58:59], v[144:145], v[16:17] op_sel_hi:[1,0,1]
	ds_read_b128 v[44:47], v32 offset:384
	ds_read_b128 v[48:51], v32 offset:400
	ds_read_b128 v[52:55], v32 offset:416
	ds_read_b128 v[56:59], v32 offset:432
	s_waitcnt lgkmcnt(4)
	v_pk_fma_f32 v[28:29], v[60:61], v[144:145], v[28:29] op_sel:[0,1,0] op_sel_hi:[1,1,1]
	v_pk_fma_f32 v[30:31], v[62:63], v[144:145], v[30:31] op_sel:[0,1,0] op_sel_hi:[1,1,1]
	v_pk_fma_f32 v[26:27], v[64:65], v[144:145], v[26:27] op_sel:[0,1,0] op_sel_hi:[1,1,1]
	v_pk_fma_f32 v[24:25], v[66:67], v[144:145], v[24:25] op_sel:[0,1,0] op_sel_hi:[1,1,1]
	v_pk_fma_f32 v[22:23], v[68:69], v[144:145], v[22:23] op_sel:[0,1,0] op_sel_hi:[1,1,1]
	v_pk_fma_f32 v[20:21], v[70:71], v[144:145], v[20:21] op_sel:[0,1,0] op_sel_hi:[1,1,1]
	v_pk_fma_f32 v[18:19], v[72:73], v[144:145], v[18:19] op_sel:[0,1,0] op_sel_hi:[1,1,1]
	v_pk_fma_f32 v[16:17], v[74:75], v[144:145], v[16:17] op_sel:[0,1,0] op_sel_hi:[1,1,1]
	ds_read_b128 v[60:63], v32 offset:448
	ds_read_b128 v[64:67], v32 offset:464
	ds_read_b128 v[68:71], v32 offset:480
	ds_read_b128 v[72:75], v32 offset:496
	s_waitcnt lgkmcnt(4)
	v_pk_fma_f32 v[28:29], v[44:45], v[146:147], v[28:29] op_sel_hi:[1,0,1]
	v_pk_fma_f32 v[30:31], v[46:47], v[146:147], v[30:31] op_sel_hi:[1,0,1]
	v_pk_fma_f32 v[26:27], v[48:49], v[146:147], v[26:27] op_sel_hi:[1,0,1]
	v_pk_fma_f32 v[24:25], v[50:51], v[146:147], v[24:25] op_sel_hi:[1,0,1]
	v_pk_fma_f32 v[22:23], v[52:53], v[146:147], v[22:23] op_sel_hi:[1,0,1]
	v_pk_fma_f32 v[20:21], v[54:55], v[146:147], v[20:21] op_sel_hi:[1,0,1]
	v_pk_fma_f32 v[18:19], v[56:57], v[146:147], v[18:19] op_sel_hi:[1,0,1]
	v_pk_fma_f32 v[16:17], v[58:59], v[146:147], v[16:17] op_sel_hi:[1,0,1]
	ds_read_b128 v[44:47], v32 offset:512
	ds_read_b128 v[48:51], v32 offset:528
	ds_read_b128 v[52:55], v32 offset:544
	ds_read_b128 v[56:59], v32 offset:560
	s_waitcnt lgkmcnt(4)
	v_pk_fma_f32 v[28:29], v[60:61], v[146:147], v[28:29] op_sel:[0,1,0] op_sel_hi:[1,1,1]
	v_pk_fma_f32 v[30:31], v[62:63], v[146:147], v[30:31] op_sel:[0,1,0] op_sel_hi:[1,1,1]
	v_pk_fma_f32 v[26:27], v[64:65], v[146:147], v[26:27] op_sel:[0,1,0] op_sel_hi:[1,1,1]
	v_pk_fma_f32 v[24:25], v[66:67], v[146:147], v[24:25] op_sel:[0,1,0] op_sel_hi:[1,1,1]
	v_pk_fma_f32 v[22:23], v[68:69], v[146:147], v[22:23] op_sel:[0,1,0] op_sel_hi:[1,1,1]
	v_pk_fma_f32 v[20:21], v[70:71], v[146:147], v[20:21] op_sel:[0,1,0] op_sel_hi:[1,1,1]
	v_pk_fma_f32 v[18:19], v[72:73], v[146:147], v[18:19] op_sel:[0,1,0] op_sel_hi:[1,1,1]
	v_pk_fma_f32 v[16:17], v[74:75], v[146:147], v[16:17] op_sel:[0,1,0] op_sel_hi:[1,1,1]
	ds_read_b128 v[60:63], v32 offset:576
	ds_read_b128 v[64:67], v32 offset:592
	ds_read_b128 v[68:71], v32 offset:608
	ds_read_b128 v[72:75], v32 offset:624
	s_waitcnt lgkmcnt(4)
	v_pk_fma_f32 v[28:29], v[44:45], v[148:149], v[28:29] op_sel_hi:[1,0,1]
	v_pk_fma_f32 v[30:31], v[46:47], v[148:149], v[30:31] op_sel_hi:[1,0,1]
	v_pk_fma_f32 v[26:27], v[48:49], v[148:149], v[26:27] op_sel_hi:[1,0,1]
	v_pk_fma_f32 v[24:25], v[50:51], v[148:149], v[24:25] op_sel_hi:[1,0,1]
	v_pk_fma_f32 v[22:23], v[52:53], v[148:149], v[22:23] op_sel_hi:[1,0,1]
	v_pk_fma_f32 v[20:21], v[54:55], v[148:149], v[20:21] op_sel_hi:[1,0,1]
	v_pk_fma_f32 v[18:19], v[56:57], v[148:149], v[18:19] op_sel_hi:[1,0,1]
	v_pk_fma_f32 v[16:17], v[58:59], v[148:149], v[16:17] op_sel_hi:[1,0,1]
	ds_read_b128 v[44:47], v32 offset:640
	ds_read_b128 v[48:51], v32 offset:656
	ds_read_b128 v[52:55], v32 offset:672
	ds_read_b128 v[56:59], v32 offset:688
	s_waitcnt lgkmcnt(4)
	v_pk_fma_f32 v[28:29], v[60:61], v[148:149], v[28:29] op_sel:[0,1,0] op_sel_hi:[1,1,1]
	v_pk_fma_f32 v[30:31], v[62:63], v[148:149], v[30:31] op_sel:[0,1,0] op_sel_hi:[1,1,1]
	v_pk_fma_f32 v[26:27], v[64:65], v[148:149], v[26:27] op_sel:[0,1,0] op_sel_hi:[1,1,1]
	v_pk_fma_f32 v[24:25], v[66:67], v[148:149], v[24:25] op_sel:[0,1,0] op_sel_hi:[1,1,1]
	v_pk_fma_f32 v[22:23], v[68:69], v[148:149], v[22:23] op_sel:[0,1,0] op_sel_hi:[1,1,1]
	v_pk_fma_f32 v[20:21], v[70:71], v[148:149], v[20:21] op_sel:[0,1,0] op_sel_hi:[1,1,1]
	v_pk_fma_f32 v[18:19], v[72:73], v[148:149], v[18:19] op_sel:[0,1,0] op_sel_hi:[1,1,1]
	v_pk_fma_f32 v[16:17], v[74:75], v[148:149], v[16:17] op_sel:[0,1,0] op_sel_hi:[1,1,1]
	ds_read_b128 v[60:63], v32 offset:704
	ds_read_b128 v[64:67], v32 offset:720
	ds_read_b128 v[68:71], v32 offset:736
	ds_read_b128 v[72:75], v32 offset:752
	s_waitcnt lgkmcnt(4)
	v_pk_fma_f32 v[28:29], v[44:45], v[150:151], v[28:29] op_sel_hi:[1,0,1]
	v_pk_fma_f32 v[30:31], v[46:47], v[150:151], v[30:31] op_sel_hi:[1,0,1]
	v_pk_fma_f32 v[26:27], v[48:49], v[150:151], v[26:27] op_sel_hi:[1,0,1]
	v_pk_fma_f32 v[24:25], v[50:51], v[150:151], v[24:25] op_sel_hi:[1,0,1]
	v_pk_fma_f32 v[22:23], v[52:53], v[150:151], v[22:23] op_sel_hi:[1,0,1]
	v_pk_fma_f32 v[20:21], v[54:55], v[150:151], v[20:21] op_sel_hi:[1,0,1]
	v_pk_fma_f32 v[18:19], v[56:57], v[150:151], v[18:19] op_sel_hi:[1,0,1]
	v_pk_fma_f32 v[16:17], v[58:59], v[150:151], v[16:17] op_sel_hi:[1,0,1]
	ds_read_b128 v[44:47], v32 offset:768
	ds_read_b128 v[48:51], v32 offset:784
	ds_read_b128 v[52:55], v32 offset:800
	ds_read_b128 v[56:59], v32 offset:816
	s_waitcnt lgkmcnt(4)
	v_pk_fma_f32 v[28:29], v[60:61], v[150:151], v[28:29] op_sel:[0,1,0] op_sel_hi:[1,1,1]
	v_pk_fma_f32 v[30:31], v[62:63], v[150:151], v[30:31] op_sel:[0,1,0] op_sel_hi:[1,1,1]
	v_pk_fma_f32 v[26:27], v[64:65], v[150:151], v[26:27] op_sel:[0,1,0] op_sel_hi:[1,1,1]
	v_pk_fma_f32 v[24:25], v[66:67], v[150:151], v[24:25] op_sel:[0,1,0] op_sel_hi:[1,1,1]
	v_pk_fma_f32 v[22:23], v[68:69], v[150:151], v[22:23] op_sel:[0,1,0] op_sel_hi:[1,1,1]
	v_pk_fma_f32 v[20:21], v[70:71], v[150:151], v[20:21] op_sel:[0,1,0] op_sel_hi:[1,1,1]
	v_pk_fma_f32 v[18:19], v[72:73], v[150:151], v[18:19] op_sel:[0,1,0] op_sel_hi:[1,1,1]
	v_pk_fma_f32 v[16:17], v[74:75], v[150:151], v[16:17] op_sel:[0,1,0] op_sel_hi:[1,1,1]
	ds_read_b128 v[60:63], v32 offset:832
	ds_read_b128 v[64:67], v32 offset:848
	ds_read_b128 v[68:71], v32 offset:864
	ds_read_b128 v[72:75], v32 offset:880
	s_waitcnt lgkmcnt(4)
	v_pk_fma_f32 v[28:29], v[44:45], v[152:153], v[28:29] op_sel_hi:[1,0,1]
	v_pk_fma_f32 v[30:31], v[46:47], v[152:153], v[30:31] op_sel_hi:[1,0,1]
	v_pk_fma_f32 v[26:27], v[48:49], v[152:153], v[26:27] op_sel_hi:[1,0,1]
	v_pk_fma_f32 v[24:25], v[50:51], v[152:153], v[24:25] op_sel_hi:[1,0,1]
	v_pk_fma_f32 v[22:23], v[52:53], v[152:153], v[22:23] op_sel_hi:[1,0,1]
	v_pk_fma_f32 v[20:21], v[54:55], v[152:153], v[20:21] op_sel_hi:[1,0,1]
	v_pk_fma_f32 v[18:19], v[56:57], v[152:153], v[18:19] op_sel_hi:[1,0,1]
	v_pk_fma_f32 v[16:17], v[58:59], v[152:153], v[16:17] op_sel_hi:[1,0,1]
	ds_read_b128 v[44:47], v32 offset:896
	ds_read_b128 v[48:51], v32 offset:912
	ds_read_b128 v[52:55], v32 offset:928
	ds_read_b128 v[56:59], v32 offset:944
	s_waitcnt lgkmcnt(4)
	v_pk_fma_f32 v[28:29], v[60:61], v[152:153], v[28:29] op_sel:[0,1,0] op_sel_hi:[1,1,1]
	v_pk_fma_f32 v[30:31], v[62:63], v[152:153], v[30:31] op_sel:[0,1,0] op_sel_hi:[1,1,1]
	v_pk_fma_f32 v[26:27], v[64:65], v[152:153], v[26:27] op_sel:[0,1,0] op_sel_hi:[1,1,1]
	v_pk_fma_f32 v[24:25], v[66:67], v[152:153], v[24:25] op_sel:[0,1,0] op_sel_hi:[1,1,1]
	v_pk_fma_f32 v[22:23], v[68:69], v[152:153], v[22:23] op_sel:[0,1,0] op_sel_hi:[1,1,1]
	v_pk_fma_f32 v[20:21], v[70:71], v[152:153], v[20:21] op_sel:[0,1,0] op_sel_hi:[1,1,1]
	v_pk_fma_f32 v[18:19], v[72:73], v[152:153], v[18:19] op_sel:[0,1,0] op_sel_hi:[1,1,1]
	v_pk_fma_f32 v[16:17], v[74:75], v[152:153], v[16:17] op_sel:[0,1,0] op_sel_hi:[1,1,1]
	ds_read_b128 v[60:63], v32 offset:960
	ds_read_b128 v[64:67], v32 offset:976
	ds_read_b128 v[68:71], v32 offset:992
	ds_read_b128 v[72:75], v32 offset:1008
	s_waitcnt lgkmcnt(4)
	v_pk_fma_f32 v[28:29], v[44:45], v[154:155], v[28:29] op_sel_hi:[1,0,1]
	v_pk_fma_f32 v[30:31], v[46:47], v[154:155], v[30:31] op_sel_hi:[1,0,1]
	v_pk_fma_f32 v[26:27], v[48:49], v[154:155], v[26:27] op_sel_hi:[1,0,1]
	v_pk_fma_f32 v[24:25], v[50:51], v[154:155], v[24:25] op_sel_hi:[1,0,1]
	v_pk_fma_f32 v[22:23], v[52:53], v[154:155], v[22:23] op_sel_hi:[1,0,1]
	v_pk_fma_f32 v[20:21], v[54:55], v[154:155], v[20:21] op_sel_hi:[1,0,1]
	v_pk_fma_f32 v[18:19], v[56:57], v[154:155], v[18:19] op_sel_hi:[1,0,1]
	v_pk_fma_f32 v[16:17], v[58:59], v[154:155], v[16:17] op_sel_hi:[1,0,1]
	s_waitcnt lgkmcnt(0)
	v_pk_fma_f32 v[28:29], v[60:61], v[154:155], v[28:29] op_sel:[0,1,0] op_sel_hi:[1,1,1]
	v_pk_fma_f32 v[30:31], v[62:63], v[154:155], v[30:31] op_sel:[0,1,0] op_sel_hi:[1,1,1]
	v_pk_fma_f32 v[26:27], v[64:65], v[154:155], v[26:27] op_sel:[0,1,0] op_sel_hi:[1,1,1]
	v_pk_fma_f32 v[24:25], v[66:67], v[154:155], v[24:25] op_sel:[0,1,0] op_sel_hi:[1,1,1]
	v_pk_fma_f32 v[22:23], v[68:69], v[154:155], v[22:23] op_sel:[0,1,0] op_sel_hi:[1,1,1]
	v_pk_fma_f32 v[20:21], v[70:71], v[154:155], v[20:21] op_sel:[0,1,0] op_sel_hi:[1,1,1]
	v_pk_fma_f32 v[18:19], v[72:73], v[154:155], v[18:19] op_sel:[0,1,0] op_sel_hi:[1,1,1]
	v_pk_fma_f32 v[16:17], v[74:75], v[154:155], v[16:17] op_sel:[0,1,0] op_sel_hi:[1,1,1]
	v_add_u32_e32 v32, 0x400, v32
	s_add_i32 s42, s42, -1
	s_cmp_lg_u32 s42, 0
	s_cbranch_scc1 .Lada_loop
	global_load_dword v140, v[76:77], off nt
	v_lshl_add_u64 v[76:77], v[76:77], 0, s[0:1]
	global_load_dword v141, v[76:77], off nt
	v_lshl_add_u64 v[76:77], v[76:77], 0, s[0:1]
	global_load_dword v142, v[76:77], off nt
	v_lshl_add_u64 v[76:77], v[76:77], 0, s[0:1]
	global_load_dword v143, v[76:77], off nt
	v_lshl_add_u64 v[76:77], v[76:77], 0, s[0:1]
	global_load_dword v144, v[76:77], off nt
	v_lshl_add_u64 v[76:77], v[76:77], 0, s[0:1]
	global_load_dword v145, v[76:77], off nt
	v_lshl_add_u64 v[76:77], v[76:77], 0, s[0:1]
	global_load_dword v146, v[76:77], off nt
	v_lshl_add_u64 v[76:77], v[76:77], 0, s[0:1]
	global_load_dword v147, v[76:77], off nt
	v_lshl_add_u64 v[76:77], v[76:77], 0, s[0:1]
	global_load_dword v148, v[76:77], off nt
	v_lshl_add_u64 v[76:77], v[76:77], 0, s[0:1]
	global_load_dword v149, v[76:77], off nt
	v_lshl_add_u64 v[76:77], v[76:77], 0, s[0:1]
	global_load_dword v150, v[76:77], off nt
	v_lshl_add_u64 v[76:77], v[76:77], 0, s[0:1]
	global_load_dword v151, v[76:77], off nt
	v_lshl_add_u64 v[76:77], v[76:77], 0, s[0:1]
	global_load_dword v152, v[76:77], off nt
	v_lshl_add_u64 v[76:77], v[76:77], 0, s[0:1]
	global_load_dword v153, v[76:77], off nt
	v_lshl_add_u64 v[76:77], v[76:77], 0, s[0:1]
	global_load_dword v154, v[76:77], off nt
	v_lshl_add_u64 v[76:77], v[76:77], 0, s[0:1]
	global_load_dword v155, v[76:77], off nt
	v_lshl_add_u64 v[76:77], v[76:77], 0, s[0:1]
	s_waitcnt vmcnt(16)
	ds_read_b128 v[44:47], v32 offset:0
	ds_read_b128 v[48:51], v32 offset:16
	ds_read_b128 v[52:55], v32 offset:32
	ds_read_b128 v[56:59], v32 offset:48
	ds_read_b128 v[60:63], v32 offset:64
	ds_read_b128 v[64:67], v32 offset:80
	ds_read_b128 v[68:71], v32 offset:96
	ds_read_b128 v[72:75], v32 offset:112
	s_waitcnt lgkmcnt(4)
	v_pk_fma_f32 v[28:29], v[44:45], v[104:105], v[28:29] op_sel_hi:[1,0,1]
	v_pk_fma_f32 v[30:31], v[46:47], v[104:105], v[30:31] op_sel_hi:[1,0,1]
	v_pk_fma_f32 v[26:27], v[48:49], v[104:105], v[26:27] op_sel_hi:[1,0,1]
	v_pk_fma_f32 v[24:25], v[50:51], v[104:105], v[24:25] op_sel_hi:[1,0,1]
	v_pk_fma_f32 v[22:23], v[52:53], v[104:105], v[22:23] op_sel_hi:[1,0,1]
	v_pk_fma_f32 v[20:21], v[54:55], v[104:105], v[20:21] op_sel_hi:[1,0,1]
	v_pk_fma_f32 v[18:19], v[56:57], v[104:105], v[18:19] op_sel_hi:[1,0,1]
	v_pk_fma_f32 v[16:17], v[58:59], v[104:105], v[16:17] op_sel_hi:[1,0,1]
	ds_read_b128 v[44:47], v32 offset:128
	ds_read_b128 v[48:51], v32 offset:144
	ds_read_b128 v[52:55], v32 offset:160
	ds_read_b128 v[56:59], v32 offset:176
	s_waitcnt lgkmcnt(4)
	v_pk_fma_f32 v[28:29], v[60:61], v[104:105], v[28:29] op_sel:[0,1,0] op_sel_hi:[1,1,1]
	v_pk_fma_f32 v[30:31], v[62:63], v[104:105], v[30:31] op_sel:[0,1,0] op_sel_hi:[1,1,1]
	v_pk_fma_f32 v[26:27], v[64:65], v[104:105], v[26:27] op_sel:[0,1,0] op_sel_hi:[1,1,1]
	v_pk_fma_f32 v[24:25], v[66:67], v[104:105], v[24:25] op_sel:[0,1,0] op_sel_hi:[1,1,1]
	v_pk_fma_f32 v[22:23], v[68:69], v[104:105], v[22:23] op_sel:[0,1,0] op_sel_hi:[1,1,1]
	v_pk_fma_f32 v[20:21], v[70:71], v[104:105], v[20:21] op_sel:[0,1,0] op_sel_hi:[1,1,1]
	v_pk_fma_f32 v[18:19], v[72:73], v[104:105], v[18:19] op_sel:[0,1,0] op_sel_hi:[1,1,1]
	v_pk_fma_f32 v[16:17], v[74:75], v[104:105], v[16:17] op_sel:[0,1,0] op_sel_hi:[1,1,1]
	ds_read_b128 v[60:63], v32 offset:192
	ds_read_b128 v[64:67], v32 offset:208
	ds_read_b128 v[68:71], v32 offset:224
	ds_read_b128 v[72:75], v32 offset:240
	s_waitcnt lgkmcnt(4)
	v_pk_fma_f32 v[28:29], v[44:45], v[106:107], v[28:29] op_sel_hi:[1,0,1]
	v_pk_fma_f32 v[30:31], v[46:47], v[106:107], v[30:31] op_sel_hi:[1,0,1]
	v_pk_fma_f32 v[26:27], v[48:49], v[106:107], v[26:27] op_sel_hi:[1,0,1]
	v_pk_fma_f32 v[24:25], v[50:51], v[106:107], v[24:25] op_sel_hi:[1,0,1]
	v_pk_fma_f32 v[22:23], v[52:53], v[106:107], v[22:23] op_sel_hi:[1,0,1]
	v_pk_fma_f32 v[20:21], v[54:55], v[106:107], v[20:21] op_sel_hi:[1,0,1]
	v_pk_fma_f32 v[18:19], v[56:57], v[106:107], v[18:19] op_sel_hi:[1,0,1]
	v_pk_fma_f32 v[16:17], v[58:59], v[106:107], v[16:17] op_sel_hi:[1,0,1]
	ds_read_b128 v[44:47], v32 offset:256
	ds_read_b128 v[48:51], v32 offset:272
	ds_read_b128 v[52:55], v32 offset:288
	ds_read_b128 v[56:59], v32 offset:304
	s_waitcnt lgkmcnt(4)
	v_pk_fma_f32 v[28:29], v[60:61], v[106:107], v[28:29] op_sel:[0,1,0] op_sel_hi:[1,1,1]
	v_pk_fma_f32 v[30:31], v[62:63], v[106:107], v[30:31] op_sel:[0,1,0] op_sel_hi:[1,1,1]
	v_pk_fma_f32 v[26:27], v[64:65], v[106:107], v[26:27] op_sel:[0,1,0] op_sel_hi:[1,1,1]
	v_pk_fma_f32 v[24:25], v[66:67], v[106:107], v[24:25] op_sel:[0,1,0] op_sel_hi:[1,1,1]
	v_pk_fma_f32 v[22:23], v[68:69], v[106:107], v[22:23] op_sel:[0,1,0] op_sel_hi:[1,1,1]
	v_pk_fma_f32 v[20:21], v[70:71], v[106:107], v[20:21] op_sel:[0,1,0] op_sel_hi:[1,1,1]
	v_pk_fma_f32 v[18:19], v[72:73], v[106:107], v[18:19] op_sel:[0,1,0] op_sel_hi:[1,1,1]
	v_pk_fma_f32 v[16:17], v[74:75], v[106:107], v[16:17] op_sel:[0,1,0] op_sel_hi:[1,1,1]
	ds_read_b128 v[60:63], v32 offset:320
	ds_read_b128 v[64:67], v32 offset:336
	ds_read_b128 v[68:71], v32 offset:352
	ds_read_b128 v[72:75], v32 offset:368
	s_waitcnt lgkmcnt(4)
	v_pk_fma_f32 v[28:29], v[44:45], v[108:109], v[28:29] op_sel_hi:[1,0,1]
	v_pk_fma_f32 v[30:31], v[46:47], v[108:109], v[30:31] op_sel_hi:[1,0,1]
	v_pk_fma_f32 v[26:27], v[48:49], v[108:109], v[26:27] op_sel_hi:[1,0,1]
	v_pk_fma_f32 v[24:25], v[50:51], v[108:109], v[24:25] op_sel_hi:[1,0,1]
	v_pk_fma_f32 v[22:23], v[52:53], v[108:109], v[22:23] op_sel_hi:[1,0,1]
	v_pk_fma_f32 v[20:21], v[54:55], v[108:109], v[20:21] op_sel_hi:[1,0,1]
	v_pk_fma_f32 v[18:19], v[56:57], v[108:109], v[18:19] op_sel_hi:[1,0,1]
	v_pk_fma_f32 v[16:17], v[58:59], v[108:109], v[16:17] op_sel_hi:[1,0,1]
	ds_read_b128 v[44:47], v32 offset:384
	ds_read_b128 v[48:51], v32 offset:400
	ds_read_b128 v[52:55], v32 offset:416
	ds_read_b128 v[56:59], v32 offset:432
	s_waitcnt lgkmcnt(4)
	v_pk_fma_f32 v[28:29], v[60:61], v[108:109], v[28:29] op_sel:[0,1,0] op_sel_hi:[1,1,1]
	v_pk_fma_f32 v[30:31], v[62:63], v[108:109], v[30:31] op_sel:[0,1,0] op_sel_hi:[1,1,1]
	v_pk_fma_f32 v[26:27], v[64:65], v[108:109], v[26:27] op_sel:[0,1,0] op_sel_hi:[1,1,1]
	v_pk_fma_f32 v[24:25], v[66:67], v[108:109], v[24:25] op_sel:[0,1,0] op_sel_hi:[1,1,1]
	v_pk_fma_f32 v[22:23], v[68:69], v[108:109], v[22:23] op_sel:[0,1,0] op_sel_hi:[1,1,1]
	v_pk_fma_f32 v[20:21], v[70:71], v[108:109], v[20:21] op_sel:[0,1,0] op_sel_hi:[1,1,1]
	v_pk_fma_f32 v[18:19], v[72:73], v[108:109], v[18:19] op_sel:[0,1,0] op_sel_hi:[1,1,1]
	v_pk_fma_f32 v[16:17], v[74:75], v[108:109], v[16:17] op_sel:[0,1,0] op_sel_hi:[1,1,1]
	ds_read_b128 v[60:63], v32 offset:448
	ds_read_b128 v[64:67], v32 offset:464
	ds_read_b128 v[68:71], v32 offset:480
	ds_read_b128 v[72:75], v32 offset:496
	s_waitcnt lgkmcnt(4)
	v_pk_fma_f32 v[28:29], v[44:45], v[110:111], v[28:29] op_sel_hi:[1,0,1]
	v_pk_fma_f32 v[30:31], v[46:47], v[110:111], v[30:31] op_sel_hi:[1,0,1]
	v_pk_fma_f32 v[26:27], v[48:49], v[110:111], v[26:27] op_sel_hi:[1,0,1]
	v_pk_fma_f32 v[24:25], v[50:51], v[110:111], v[24:25] op_sel_hi:[1,0,1]
	v_pk_fma_f32 v[22:23], v[52:53], v[110:111], v[22:23] op_sel_hi:[1,0,1]
	v_pk_fma_f32 v[20:21], v[54:55], v[110:111], v[20:21] op_sel_hi:[1,0,1]
	v_pk_fma_f32 v[18:19], v[56:57], v[110:111], v[18:19] op_sel_hi:[1,0,1]
	v_pk_fma_f32 v[16:17], v[58:59], v[110:111], v[16:17] op_sel_hi:[1,0,1]
	ds_read_b128 v[44:47], v32 offset:512
	ds_read_b128 v[48:51], v32 offset:528
	ds_read_b128 v[52:55], v32 offset:544
	ds_read_b128 v[56:59], v32 offset:560
	s_waitcnt lgkmcnt(4)
	v_pk_fma_f32 v[28:29], v[60:61], v[110:111], v[28:29] op_sel:[0,1,0] op_sel_hi:[1,1,1]
	v_pk_fma_f32 v[30:31], v[62:63], v[110:111], v[30:31] op_sel:[0,1,0] op_sel_hi:[1,1,1]
	v_pk_fma_f32 v[26:27], v[64:65], v[110:111], v[26:27] op_sel:[0,1,0] op_sel_hi:[1,1,1]
	v_pk_fma_f32 v[24:25], v[66:67], v[110:111], v[24:25] op_sel:[0,1,0] op_sel_hi:[1,1,1]
	v_pk_fma_f32 v[22:23], v[68:69], v[110:111], v[22:23] op_sel:[0,1,0] op_sel_hi:[1,1,1]
	v_pk_fma_f32 v[20:21], v[70:71], v[110:111], v[20:21] op_sel:[0,1,0] op_sel_hi:[1,1,1]
	v_pk_fma_f32 v[18:19], v[72:73], v[110:111], v[18:19] op_sel:[0,1,0] op_sel_hi:[1,1,1]
	v_pk_fma_f32 v[16:17], v[74:75], v[110:111], v[16:17] op_sel:[0,1,0] op_sel_hi:[1,1,1]
	ds_read_b128 v[60:63], v32 offset:576
	ds_read_b128 v[64:67], v32 offset:592
	ds_read_b128 v[68:71], v32 offset:608
	ds_read_b128 v[72:75], v32 offset:624
	s_waitcnt lgkmcnt(4)
	v_pk_fma_f32 v[28:29], v[44:45], v[112:113], v[28:29] op_sel_hi:[1,0,1]
	v_pk_fma_f32 v[30:31], v[46:47], v[112:113], v[30:31] op_sel_hi:[1,0,1]
	v_pk_fma_f32 v[26:27], v[48:49], v[112:113], v[26:27] op_sel_hi:[1,0,1]
	v_pk_fma_f32 v[24:25], v[50:51], v[112:113], v[24:25] op_sel_hi:[1,0,1]
	v_pk_fma_f32 v[22:23], v[52:53], v[112:113], v[22:23] op_sel_hi:[1,0,1]
	v_pk_fma_f32 v[20:21], v[54:55], v[112:113], v[20:21] op_sel_hi:[1,0,1]
	v_pk_fma_f32 v[18:19], v[56:57], v[112:113], v[18:19] op_sel_hi:[1,0,1]
	v_pk_fma_f32 v[16:17], v[58:59], v[112:113], v[16:17] op_sel_hi:[1,0,1]
	ds_read_b128 v[44:47], v32 offset:640
	ds_read_b128 v[48:51], v32 offset:656
	ds_read_b128 v[52:55], v32 offset:672
	ds_read_b128 v[56:59], v32 offset:688
	s_waitcnt lgkmcnt(4)
	v_pk_fma_f32 v[28:29], v[60:61], v[112:113], v[28:29] op_sel:[0,1,0] op_sel_hi:[1,1,1]
	v_pk_fma_f32 v[30:31], v[62:63], v[112:113], v[30:31] op_sel:[0,1,0] op_sel_hi:[1,1,1]
	v_pk_fma_f32 v[26:27], v[64:65], v[112:113], v[26:27] op_sel:[0,1,0] op_sel_hi:[1,1,1]
	v_pk_fma_f32 v[24:25], v[66:67], v[112:113], v[24:25] op_sel:[0,1,0] op_sel_hi:[1,1,1]
	v_pk_fma_f32 v[22:23], v[68:69], v[112:113], v[22:23] op_sel:[0,1,0] op_sel_hi:[1,1,1]
	v_pk_fma_f32 v[20:21], v[70:71], v[112:113], v[20:21] op_sel:[0,1,0] op_sel_hi:[1,1,1]
	v_pk_fma_f32 v[18:19], v[72:73], v[112:113], v[18:19] op_sel:[0,1,0] op_sel_hi:[1,1,1]
	v_pk_fma_f32 v[16:17], v[74:75], v[112:113], v[16:17] op_sel:[0,1,0] op_sel_hi:[1,1,1]
	ds_read_b128 v[60:63], v32 offset:704
	ds_read_b128 v[64:67], v32 offset:720
	ds_read_b128 v[68:71], v32 offset:736
	ds_read_b128 v[72:75], v32 offset:752
	s_waitcnt lgkmcnt(4)
	v_pk_fma_f32 v[28:29], v[44:45], v[114:115], v[28:29] op_sel_hi:[1,0,1]
	v_pk_fma_f32 v[30:31], v[46:47], v[114:115], v[30:31] op_sel_hi:[1,0,1]
	v_pk_fma_f32 v[26:27], v[48:49], v[114:115], v[26:27] op_sel_hi:[1,0,1]
	v_pk_fma_f32 v[24:25], v[50:51], v[114:115], v[24:25] op_sel_hi:[1,0,1]
	v_pk_fma_f32 v[22:23], v[52:53], v[114:115], v[22:23] op_sel_hi:[1,0,1]
	v_pk_fma_f32 v[20:21], v[54:55], v[114:115], v[20:21] op_sel_hi:[1,0,1]
	v_pk_fma_f32 v[18:19], v[56:57], v[114:115], v[18:19] op_sel_hi:[1,0,1]
	v_pk_fma_f32 v[16:17], v[58:59], v[114:115], v[16:17] op_sel_hi:[1,0,1]
	ds_read_b128 v[44:47], v32 offset:768
	ds_read_b128 v[48:51], v32 offset:784
	ds_read_b128 v[52:55], v32 offset:800
	ds_read_b128 v[56:59], v32 offset:816
	s_waitcnt lgkmcnt(4)
	v_pk_fma_f32 v[28:29], v[60:61], v[114:115], v[28:29] op_sel:[0,1,0] op_sel_hi:[1,1,1]
	v_pk_fma_f32 v[30:31], v[62:63], v[114:115], v[30:31] op_sel:[0,1,0] op_sel_hi:[1,1,1]
	v_pk_fma_f32 v[26:27], v[64:65], v[114:115], v[26:27] op_sel:[0,1,0] op_sel_hi:[1,1,1]
	v_pk_fma_f32 v[24:25], v[66:67], v[114:115], v[24:25] op_sel:[0,1,0] op_sel_hi:[1,1,1]
	v_pk_fma_f32 v[22:23], v[68:69], v[114:115], v[22:23] op_sel:[0,1,0] op_sel_hi:[1,1,1]
	v_pk_fma_f32 v[20:21], v[70:71], v[114:115], v[20:21] op_sel:[0,1,0] op_sel_hi:[1,1,1]
	v_pk_fma_f32 v[18:19], v[72:73], v[114:115], v[18:19] op_sel:[0,1,0] op_sel_hi:[1,1,1]
	v_pk_fma_f32 v[16:17], v[74:75], v[114:115], v[16:17] op_sel:[0,1,0] op_sel_hi:[1,1,1]
	ds_read_b128 v[60:63], v32 offset:832
	ds_read_b128 v[64:67], v32 offset:848
	ds_read_b128 v[68:71], v32 offset:864
	ds_read_b128 v[72:75], v32 offset:880
	s_waitcnt lgkmcnt(4)
	v_pk_fma_f32 v[28:29], v[44:45], v[116:117], v[28:29] op_sel_hi:[1,0,1]
	v_pk_fma_f32 v[30:31], v[46:47], v[116:117], v[30:31] op_sel_hi:[1,0,1]
	v_pk_fma_f32 v[26:27], v[48:49], v[116:117], v[26:27] op_sel_hi:[1,0,1]
	v_pk_fma_f32 v[24:25], v[50:51], v[116:117], v[24:25] op_sel_hi:[1,0,1]
	v_pk_fma_f32 v[22:23], v[52:53], v[116:117], v[22:23] op_sel_hi:[1,0,1]
	v_pk_fma_f32 v[20:21], v[54:55], v[116:117], v[20:21] op_sel_hi:[1,0,1]
	v_pk_fma_f32 v[18:19], v[56:57], v[116:117], v[18:19] op_sel_hi:[1,0,1]
	v_pk_fma_f32 v[16:17], v[58:59], v[116:117], v[16:17] op_sel_hi:[1,0,1]
	ds_read_b128 v[44:47], v32 offset:896
	ds_read_b128 v[48:51], v32 offset:912
	ds_read_b128 v[52:55], v32 offset:928
	ds_read_b128 v[56:59], v32 offset:944
	s_waitcnt lgkmcnt(4)
	v_pk_fma_f32 v[28:29], v[60:61], v[116:117], v[28:29] op_sel:[0,1,0] op_sel_hi:[1,1,1]
	v_pk_fma_f32 v[30:31], v[62:63], v[116:117], v[30:31] op_sel:[0,1,0] op_sel_hi:[1,1,1]
	v_pk_fma_f32 v[26:27], v[64:65], v[116:117], v[26:27] op_sel:[0,1,0] op_sel_hi:[1,1,1]
	v_pk_fma_f32 v[24:25], v[66:67], v[116:117], v[24:25] op_sel:[0,1,0] op_sel_hi:[1,1,1]
	v_pk_fma_f32 v[22:23], v[68:69], v[116:117], v[22:23] op_sel:[0,1,0] op_sel_hi:[1,1,1]
	v_pk_fma_f32 v[20:21], v[70:71], v[116:117], v[20:21] op_sel:[0,1,0] op_sel_hi:[1,1,1]
	v_pk_fma_f32 v[18:19], v[72:73], v[116:117], v[18:19] op_sel:[0,1,0] op_sel_hi:[1,1,1]
	v_pk_fma_f32 v[16:17], v[74:75], v[116:117], v[16:17] op_sel:[0,1,0] op_sel_hi:[1,1,1]
	ds_read_b128 v[60:63], v32 offset:960
	ds_read_b128 v[64:67], v32 offset:976
	ds_read_b128 v[68:71], v32 offset:992
	ds_read_b128 v[72:75], v32 offset:1008
	s_waitcnt lgkmcnt(4)
	v_pk_fma_f32 v[28:29], v[44:45], v[118:119], v[28:29] op_sel_hi:[1,0,1]
	v_pk_fma_f32 v[30:31], v[46:47], v[118:119], v[30:31] op_sel_hi:[1,0,1]
	v_pk_fma_f32 v[26:27], v[48:49], v[118:119], v[26:27] op_sel_hi:[1,0,1]
	v_pk_fma_f32 v[24:25], v[50:51], v[118:119], v[24:25] op_sel_hi:[1,0,1]
	v_pk_fma_f32 v[22:23], v[52:53], v[118:119], v[22:23] op_sel_hi:[1,0,1]
	v_pk_fma_f32 v[20:21], v[54:55], v[118:119], v[20:21] op_sel_hi:[1,0,1]
	v_pk_fma_f32 v[18:19], v[56:57], v[118:119], v[18:19] op_sel_hi:[1,0,1]
	v_pk_fma_f32 v[16:17], v[58:59], v[118:119], v[16:17] op_sel_hi:[1,0,1]
	s_waitcnt lgkmcnt(0)
	v_pk_fma_f32 v[28:29], v[60:61], v[118:119], v[28:29] op_sel:[0,1,0] op_sel_hi:[1,1,1]
	v_pk_fma_f32 v[30:31], v[62:63], v[118:119], v[30:31] op_sel:[0,1,0] op_sel_hi:[1,1,1]
	v_pk_fma_f32 v[26:27], v[64:65], v[118:119], v[26:27] op_sel:[0,1,0] op_sel_hi:[1,1,1]
	v_pk_fma_f32 v[24:25], v[66:67], v[118:119], v[24:25] op_sel:[0,1,0] op_sel_hi:[1,1,1]
	v_pk_fma_f32 v[22:23], v[68:69], v[118:119], v[22:23] op_sel:[0,1,0] op_sel_hi:[1,1,1]
	v_pk_fma_f32 v[20:21], v[70:71], v[118:119], v[20:21] op_sel:[0,1,0] op_sel_hi:[1,1,1]
	v_pk_fma_f32 v[18:19], v[72:73], v[118:119], v[18:19] op_sel:[0,1,0] op_sel_hi:[1,1,1]
	v_pk_fma_f32 v[16:17], v[74:75], v[118:119], v[16:17] op_sel:[0,1,0] op_sel_hi:[1,1,1]
	v_add_u32_e32 v32, 0x400, v32
	s_waitcnt vmcnt(0)
	ds_read_b128 v[44:47], v32 offset:0
	ds_read_b128 v[48:51], v32 offset:16
	ds_read_b128 v[52:55], v32 offset:32
	ds_read_b128 v[56:59], v32 offset:48
	ds_read_b128 v[60:63], v32 offset:64
	ds_read_b128 v[64:67], v32 offset:80
	ds_read_b128 v[68:71], v32 offset:96
	ds_read_b128 v[72:75], v32 offset:112
	s_waitcnt lgkmcnt(4)
	v_pk_fma_f32 v[28:29], v[44:45], v[140:141], v[28:29] op_sel_hi:[1,0,1]
	v_pk_fma_f32 v[30:31], v[46:47], v[140:141], v[30:31] op_sel_hi:[1,0,1]
	v_pk_fma_f32 v[26:27], v[48:49], v[140:141], v[26:27] op_sel_hi:[1,0,1]
	v_pk_fma_f32 v[24:25], v[50:51], v[140:141], v[24:25] op_sel_hi:[1,0,1]
	v_pk_fma_f32 v[22:23], v[52:53], v[140:141], v[22:23] op_sel_hi:[1,0,1]
	v_pk_fma_f32 v[20:21], v[54:55], v[140:141], v[20:21] op_sel_hi:[1,0,1]
	v_pk_fma_f32 v[18:19], v[56:57], v[140:141], v[18:19] op_sel_hi:[1,0,1]
	v_pk_fma_f32 v[16:17], v[58:59], v[140:141], v[16:17] op_sel_hi:[1,0,1]
	ds_read_b128 v[44:47], v32 offset:128
	ds_read_b128 v[48:51], v32 offset:144
	ds_read_b128 v[52:55], v32 offset:160
	ds_read_b128 v[56:59], v32 offset:176
	s_waitcnt lgkmcnt(4)
	v_pk_fma_f32 v[28:29], v[60:61], v[140:141], v[28:29] op_sel:[0,1,0] op_sel_hi:[1,1,1]
	v_pk_fma_f32 v[30:31], v[62:63], v[140:141], v[30:31] op_sel:[0,1,0] op_sel_hi:[1,1,1]
	v_pk_fma_f32 v[26:27], v[64:65], v[140:141], v[26:27] op_sel:[0,1,0] op_sel_hi:[1,1,1]
	v_pk_fma_f32 v[24:25], v[66:67], v[140:141], v[24:25] op_sel:[0,1,0] op_sel_hi:[1,1,1]
	v_pk_fma_f32 v[22:23], v[68:69], v[140:141], v[22:23] op_sel:[0,1,0] op_sel_hi:[1,1,1]
	v_pk_fma_f32 v[20:21], v[70:71], v[140:141], v[20:21] op_sel:[0,1,0] op_sel_hi:[1,1,1]
	v_pk_fma_f32 v[18:19], v[72:73], v[140:141], v[18:19] op_sel:[0,1,0] op_sel_hi:[1,1,1]
	v_pk_fma_f32 v[16:17], v[74:75], v[140:141], v[16:17] op_sel:[0,1,0] op_sel_hi:[1,1,1]
	ds_read_b128 v[60:63], v32 offset:192
	ds_read_b128 v[64:67], v32 offset:208
	ds_read_b128 v[68:71], v32 offset:224
	ds_read_b128 v[72:75], v32 offset:240
	s_waitcnt lgkmcnt(4)
	v_pk_fma_f32 v[28:29], v[44:45], v[142:143], v[28:29] op_sel_hi:[1,0,1]
	v_pk_fma_f32 v[30:31], v[46:47], v[142:143], v[30:31] op_sel_hi:[1,0,1]
	v_pk_fma_f32 v[26:27], v[48:49], v[142:143], v[26:27] op_sel_hi:[1,0,1]
	v_pk_fma_f32 v[24:25], v[50:51], v[142:143], v[24:25] op_sel_hi:[1,0,1]
	v_pk_fma_f32 v[22:23], v[52:53], v[142:143], v[22:23] op_sel_hi:[1,0,1]
	v_pk_fma_f32 v[20:21], v[54:55], v[142:143], v[20:21] op_sel_hi:[1,0,1]
	v_pk_fma_f32 v[18:19], v[56:57], v[142:143], v[18:19] op_sel_hi:[1,0,1]
	v_pk_fma_f32 v[16:17], v[58:59], v[142:143], v[16:17] op_sel_hi:[1,0,1]
	ds_read_b128 v[44:47], v32 offset:256
	ds_read_b128 v[48:51], v32 offset:272
	ds_read_b128 v[52:55], v32 offset:288
	ds_read_b128 v[56:59], v32 offset:304
	s_waitcnt lgkmcnt(4)
	v_pk_fma_f32 v[28:29], v[60:61], v[142:143], v[28:29] op_sel:[0,1,0] op_sel_hi:[1,1,1]
	v_pk_fma_f32 v[30:31], v[62:63], v[142:143], v[30:31] op_sel:[0,1,0] op_sel_hi:[1,1,1]
	v_pk_fma_f32 v[26:27], v[64:65], v[142:143], v[26:27] op_sel:[0,1,0] op_sel_hi:[1,1,1]
	v_pk_fma_f32 v[24:25], v[66:67], v[142:143], v[24:25] op_sel:[0,1,0] op_sel_hi:[1,1,1]
	v_pk_fma_f32 v[22:23], v[68:69], v[142:143], v[22:23] op_sel:[0,1,0] op_sel_hi:[1,1,1]
	v_pk_fma_f32 v[20:21], v[70:71], v[142:143], v[20:21] op_sel:[0,1,0] op_sel_hi:[1,1,1]
	v_pk_fma_f32 v[18:19], v[72:73], v[142:143], v[18:19] op_sel:[0,1,0] op_sel_hi:[1,1,1]
	v_pk_fma_f32 v[16:17], v[74:75], v[142:143], v[16:17] op_sel:[0,1,0] op_sel_hi:[1,1,1]
	ds_read_b128 v[60:63], v32 offset:320
	ds_read_b128 v[64:67], v32 offset:336
	ds_read_b128 v[68:71], v32 offset:352
	ds_read_b128 v[72:75], v32 offset:368
	s_waitcnt lgkmcnt(4)
	v_pk_fma_f32 v[28:29], v[44:45], v[144:145], v[28:29] op_sel_hi:[1,0,1]
	v_pk_fma_f32 v[30:31], v[46:47], v[144:145], v[30:31] op_sel_hi:[1,0,1]
	v_pk_fma_f32 v[26:27], v[48:49], v[144:145], v[26:27] op_sel_hi:[1,0,1]
	v_pk_fma_f32 v[24:25], v[50:51], v[144:145], v[24:25] op_sel_hi:[1,0,1]
	v_pk_fma_f32 v[22:23], v[52:53], v[144:145], v[22:23] op_sel_hi:[1,0,1]
	v_pk_fma_f32 v[20:21], v[54:55], v[144:145], v[20:21] op_sel_hi:[1,0,1]
	v_pk_fma_f32 v[18:19], v[56:57], v[144:145], v[18:19] op_sel_hi:[1,0,1]
	v_pk_fma_f32 v[16:17], v[58:59], v[144:145], v[16:17] op_sel_hi:[1,0,1]
	ds_read_b128 v[44:47], v32 offset:384
	ds_read_b128 v[48:51], v32 offset:400
	ds_read_b128 v[52:55], v32 offset:416
	ds_read_b128 v[56:59], v32 offset:432
	s_waitcnt lgkmcnt(4)
	v_pk_fma_f32 v[28:29], v[60:61], v[144:145], v[28:29] op_sel:[0,1,0] op_sel_hi:[1,1,1]
	v_pk_fma_f32 v[30:31], v[62:63], v[144:145], v[30:31] op_sel:[0,1,0] op_sel_hi:[1,1,1]
	v_pk_fma_f32 v[26:27], v[64:65], v[144:145], v[26:27] op_sel:[0,1,0] op_sel_hi:[1,1,1]
	v_pk_fma_f32 v[24:25], v[66:67], v[144:145], v[24:25] op_sel:[0,1,0] op_sel_hi:[1,1,1]
	v_pk_fma_f32 v[22:23], v[68:69], v[144:145], v[22:23] op_sel:[0,1,0] op_sel_hi:[1,1,1]
	v_pk_fma_f32 v[20:21], v[70:71], v[144:145], v[20:21] op_sel:[0,1,0] op_sel_hi:[1,1,1]
	v_pk_fma_f32 v[18:19], v[72:73], v[144:145], v[18:19] op_sel:[0,1,0] op_sel_hi:[1,1,1]
	v_pk_fma_f32 v[16:17], v[74:75], v[144:145], v[16:17] op_sel:[0,1,0] op_sel_hi:[1,1,1]
	ds_read_b128 v[60:63], v32 offset:448
	ds_read_b128 v[64:67], v32 offset:464
	ds_read_b128 v[68:71], v32 offset:480
	ds_read_b128 v[72:75], v32 offset:496
	s_waitcnt lgkmcnt(4)
	v_pk_fma_f32 v[28:29], v[44:45], v[146:147], v[28:29] op_sel_hi:[1,0,1]
	v_pk_fma_f32 v[30:31], v[46:47], v[146:147], v[30:31] op_sel_hi:[1,0,1]
	v_pk_fma_f32 v[26:27], v[48:49], v[146:147], v[26:27] op_sel_hi:[1,0,1]
	v_pk_fma_f32 v[24:25], v[50:51], v[146:147], v[24:25] op_sel_hi:[1,0,1]
	v_pk_fma_f32 v[22:23], v[52:53], v[146:147], v[22:23] op_sel_hi:[1,0,1]
	v_pk_fma_f32 v[20:21], v[54:55], v[146:147], v[20:21] op_sel_hi:[1,0,1]
	v_pk_fma_f32 v[18:19], v[56:57], v[146:147], v[18:19] op_sel_hi:[1,0,1]
	v_pk_fma_f32 v[16:17], v[58:59], v[146:147], v[16:17] op_sel_hi:[1,0,1]
	ds_read_b128 v[44:47], v32 offset:512
	ds_read_b128 v[48:51], v32 offset:528
	ds_read_b128 v[52:55], v32 offset:544
	ds_read_b128 v[56:59], v32 offset:560
	s_waitcnt lgkmcnt(4)
	v_pk_fma_f32 v[28:29], v[60:61], v[146:147], v[28:29] op_sel:[0,1,0] op_sel_hi:[1,1,1]
	v_pk_fma_f32 v[30:31], v[62:63], v[146:147], v[30:31] op_sel:[0,1,0] op_sel_hi:[1,1,1]
	v_pk_fma_f32 v[26:27], v[64:65], v[146:147], v[26:27] op_sel:[0,1,0] op_sel_hi:[1,1,1]
	v_pk_fma_f32 v[24:25], v[66:67], v[146:147], v[24:25] op_sel:[0,1,0] op_sel_hi:[1,1,1]
	v_pk_fma_f32 v[22:23], v[68:69], v[146:147], v[22:23] op_sel:[0,1,0] op_sel_hi:[1,1,1]
	v_pk_fma_f32 v[20:21], v[70:71], v[146:147], v[20:21] op_sel:[0,1,0] op_sel_hi:[1,1,1]
	v_pk_fma_f32 v[18:19], v[72:73], v[146:147], v[18:19] op_sel:[0,1,0] op_sel_hi:[1,1,1]
	v_pk_fma_f32 v[16:17], v[74:75], v[146:147], v[16:17] op_sel:[0,1,0] op_sel_hi:[1,1,1]
	ds_read_b128 v[60:63], v32 offset:576
	ds_read_b128 v[64:67], v32 offset:592
	ds_read_b128 v[68:71], v32 offset:608
	ds_read_b128 v[72:75], v32 offset:624
	s_waitcnt lgkmcnt(4)
	v_pk_fma_f32 v[28:29], v[44:45], v[148:149], v[28:29] op_sel_hi:[1,0,1]
	v_pk_fma_f32 v[30:31], v[46:47], v[148:149], v[30:31] op_sel_hi:[1,0,1]
	v_pk_fma_f32 v[26:27], v[48:49], v[148:149], v[26:27] op_sel_hi:[1,0,1]
	v_pk_fma_f32 v[24:25], v[50:51], v[148:149], v[24:25] op_sel_hi:[1,0,1]
	v_pk_fma_f32 v[22:23], v[52:53], v[148:149], v[22:23] op_sel_hi:[1,0,1]
	v_pk_fma_f32 v[20:21], v[54:55], v[148:149], v[20:21] op_sel_hi:[1,0,1]
	v_pk_fma_f32 v[18:19], v[56:57], v[148:149], v[18:19] op_sel_hi:[1,0,1]
	v_pk_fma_f32 v[16:17], v[58:59], v[148:149], v[16:17] op_sel_hi:[1,0,1]
	ds_read_b128 v[44:47], v32 offset:640
	ds_read_b128 v[48:51], v32 offset:656
	ds_read_b128 v[52:55], v32 offset:672
	ds_read_b128 v[56:59], v32 offset:688
	s_waitcnt lgkmcnt(4)
	v_pk_fma_f32 v[28:29], v[60:61], v[148:149], v[28:29] op_sel:[0,1,0] op_sel_hi:[1,1,1]
	v_pk_fma_f32 v[30:31], v[62:63], v[148:149], v[30:31] op_sel:[0,1,0] op_sel_hi:[1,1,1]
	v_pk_fma_f32 v[26:27], v[64:65], v[148:149], v[26:27] op_sel:[0,1,0] op_sel_hi:[1,1,1]
	v_pk_fma_f32 v[24:25], v[66:67], v[148:149], v[24:25] op_sel:[0,1,0] op_sel_hi:[1,1,1]
	v_pk_fma_f32 v[22:23], v[68:69], v[148:149], v[22:23] op_sel:[0,1,0] op_sel_hi:[1,1,1]
	v_pk_fma_f32 v[20:21], v[70:71], v[148:149], v[20:21] op_sel:[0,1,0] op_sel_hi:[1,1,1]
	v_pk_fma_f32 v[18:19], v[72:73], v[148:149], v[18:19] op_sel:[0,1,0] op_sel_hi:[1,1,1]
	v_pk_fma_f32 v[16:17], v[74:75], v[148:149], v[16:17] op_sel:[0,1,0] op_sel_hi:[1,1,1]
	ds_read_b128 v[60:63], v32 offset:704
	ds_read_b128 v[64:67], v32 offset:720
	ds_read_b128 v[68:71], v32 offset:736
	ds_read_b128 v[72:75], v32 offset:752
	s_waitcnt lgkmcnt(4)
	v_pk_fma_f32 v[28:29], v[44:45], v[150:151], v[28:29] op_sel_hi:[1,0,1]
	v_pk_fma_f32 v[30:31], v[46:47], v[150:151], v[30:31] op_sel_hi:[1,0,1]
	v_pk_fma_f32 v[26:27], v[48:49], v[150:151], v[26:27] op_sel_hi:[1,0,1]
	v_pk_fma_f32 v[24:25], v[50:51], v[150:151], v[24:25] op_sel_hi:[1,0,1]
	v_pk_fma_f32 v[22:23], v[52:53], v[150:151], v[22:23] op_sel_hi:[1,0,1]
	v_pk_fma_f32 v[20:21], v[54:55], v[150:151], v[20:21] op_sel_hi:[1,0,1]
	v_pk_fma_f32 v[18:19], v[56:57], v[150:151], v[18:19] op_sel_hi:[1,0,1]
	v_pk_fma_f32 v[16:17], v[58:59], v[150:151], v[16:17] op_sel_hi:[1,0,1]
	ds_read_b128 v[44:47], v32 offset:768
	ds_read_b128 v[48:51], v32 offset:784
	ds_read_b128 v[52:55], v32 offset:800
	ds_read_b128 v[56:59], v32 offset:816
	s_waitcnt lgkmcnt(4)
	v_pk_fma_f32 v[28:29], v[60:61], v[150:151], v[28:29] op_sel:[0,1,0] op_sel_hi:[1,1,1]
	v_pk_fma_f32 v[30:31], v[62:63], v[150:151], v[30:31] op_sel:[0,1,0] op_sel_hi:[1,1,1]
	v_pk_fma_f32 v[26:27], v[64:65], v[150:151], v[26:27] op_sel:[0,1,0] op_sel_hi:[1,1,1]
	v_pk_fma_f32 v[24:25], v[66:67], v[150:151], v[24:25] op_sel:[0,1,0] op_sel_hi:[1,1,1]
	v_pk_fma_f32 v[22:23], v[68:69], v[150:151], v[22:23] op_sel:[0,1,0] op_sel_hi:[1,1,1]
	v_pk_fma_f32 v[20:21], v[70:71], v[150:151], v[20:21] op_sel:[0,1,0] op_sel_hi:[1,1,1]
	v_pk_fma_f32 v[18:19], v[72:73], v[150:151], v[18:19] op_sel:[0,1,0] op_sel_hi:[1,1,1]
	v_pk_fma_f32 v[16:17], v[74:75], v[150:151], v[16:17] op_sel:[0,1,0] op_sel_hi:[1,1,1]
	ds_read_b128 v[60:63], v32 offset:832
	ds_read_b128 v[64:67], v32 offset:848
	ds_read_b128 v[68:71], v32 offset:864
	ds_read_b128 v[72:75], v32 offset:880
	s_waitcnt lgkmcnt(4)
	v_pk_fma_f32 v[28:29], v[44:45], v[152:153], v[28:29] op_sel_hi:[1,0,1]
	v_pk_fma_f32 v[30:31], v[46:47], v[152:153], v[30:31] op_sel_hi:[1,0,1]
	v_pk_fma_f32 v[26:27], v[48:49], v[152:153], v[26:27] op_sel_hi:[1,0,1]
	v_pk_fma_f32 v[24:25], v[50:51], v[152:153], v[24:25] op_sel_hi:[1,0,1]
	v_pk_fma_f32 v[22:23], v[52:53], v[152:153], v[22:23] op_sel_hi:[1,0,1]
	v_pk_fma_f32 v[20:21], v[54:55], v[152:153], v[20:21] op_sel_hi:[1,0,1]
	v_pk_fma_f32 v[18:19], v[56:57], v[152:153], v[18:19] op_sel_hi:[1,0,1]
	v_pk_fma_f32 v[16:17], v[58:59], v[152:153], v[16:17] op_sel_hi:[1,0,1]
	ds_read_b128 v[44:47], v32 offset:896
	ds_read_b128 v[48:51], v32 offset:912
	ds_read_b128 v[52:55], v32 offset:928
	ds_read_b128 v[56:59], v32 offset:944
	s_waitcnt lgkmcnt(4)
	v_pk_fma_f32 v[28:29], v[60:61], v[152:153], v[28:29] op_sel:[0,1,0] op_sel_hi:[1,1,1]
	v_pk_fma_f32 v[30:31], v[62:63], v[152:153], v[30:31] op_sel:[0,1,0] op_sel_hi:[1,1,1]
	v_pk_fma_f32 v[26:27], v[64:65], v[152:153], v[26:27] op_sel:[0,1,0] op_sel_hi:[1,1,1]
	v_pk_fma_f32 v[24:25], v[66:67], v[152:153], v[24:25] op_sel:[0,1,0] op_sel_hi:[1,1,1]
	v_pk_fma_f32 v[22:23], v[68:69], v[152:153], v[22:23] op_sel:[0,1,0] op_sel_hi:[1,1,1]
	v_pk_fma_f32 v[20:21], v[70:71], v[152:153], v[20:21] op_sel:[0,1,0] op_sel_hi:[1,1,1]
	v_pk_fma_f32 v[18:19], v[72:73], v[152:153], v[18:19] op_sel:[0,1,0] op_sel_hi:[1,1,1]
	v_pk_fma_f32 v[16:17], v[74:75], v[152:153], v[16:17] op_sel:[0,1,0] op_sel_hi:[1,1,1]
	ds_read_b128 v[60:63], v32 offset:960
	ds_read_b128 v[64:67], v32 offset:976
	ds_read_b128 v[68:71], v32 offset:992
	ds_read_b128 v[72:75], v32 offset:1008
	s_waitcnt lgkmcnt(4)
	v_pk_fma_f32 v[28:29], v[44:45], v[154:155], v[28:29] op_sel_hi:[1,0,1]
	v_pk_fma_f32 v[30:31], v[46:47], v[154:155], v[30:31] op_sel_hi:[1,0,1]
	v_pk_fma_f32 v[26:27], v[48:49], v[154:155], v[26:27] op_sel_hi:[1,0,1]
	v_pk_fma_f32 v[24:25], v[50:51], v[154:155], v[24:25] op_sel_hi:[1,0,1]
	v_pk_fma_f32 v[22:23], v[52:53], v[154:155], v[22:23] op_sel_hi:[1,0,1]
	v_pk_fma_f32 v[20:21], v[54:55], v[154:155], v[20:21] op_sel_hi:[1,0,1]
	v_pk_fma_f32 v[18:19], v[56:57], v[154:155], v[18:19] op_sel_hi:[1,0,1]
	v_pk_fma_f32 v[16:17], v[58:59], v[154:155], v[16:17] op_sel_hi:[1,0,1]
	s_waitcnt lgkmcnt(0)
	v_pk_fma_f32 v[28:29], v[60:61], v[154:155], v[28:29] op_sel:[0,1,0] op_sel_hi:[1,1,1]
	v_pk_fma_f32 v[30:31], v[62:63], v[154:155], v[30:31] op_sel:[0,1,0] op_sel_hi:[1,1,1]
	v_pk_fma_f32 v[26:27], v[64:65], v[154:155], v[26:27] op_sel:[0,1,0] op_sel_hi:[1,1,1]
	v_pk_fma_f32 v[24:25], v[66:67], v[154:155], v[24:25] op_sel:[0,1,0] op_sel_hi:[1,1,1]
	v_pk_fma_f32 v[22:23], v[68:69], v[154:155], v[22:23] op_sel:[0,1,0] op_sel_hi:[1,1,1]
	v_pk_fma_f32 v[20:21], v[70:71], v[154:155], v[20:21] op_sel:[0,1,0] op_sel_hi:[1,1,1]
	v_pk_fma_f32 v[18:19], v[72:73], v[154:155], v[18:19] op_sel:[0,1,0] op_sel_hi:[1,1,1]
	v_pk_fma_f32 v[16:17], v[74:75], v[154:155], v[16:17] op_sel:[0,1,0] op_sel_hi:[1,1,1]
	v_add_u32_e32 v32, 0x400, v32
	s_mul_i32 s0, s6, 0x2400
	s_add_i32 s0, s0, s40
	v_or_b32_e32 v14, s0, v0
	v_readlane_b32 s44, v254, 24
	v_ashrrev_i32_e32 v15, 31, v14
	v_readlane_b32 s50, v254, 30
	v_readlane_b32 s51, v254, 31
	ds_write2st64_b32 v1, v28, v29 offset1:2
	ds_write2st64_b32 v1, v26, v27 offset0:8 offset1:10
	ds_write2st64_b32 v1, v22, v23 offset0:16 offset1:18
	ds_write2st64_b32 v1, v18, v19 offset0:24 offset1:26
	ds_write2st64_b32 v1, v30, v31 offset0:4 offset1:6
	ds_write2st64_b32 v1, v24, v25 offset0:12 offset1:14
	ds_write2st64_b32 v1, v20, v21 offset0:20 offset1:22
	ds_write2st64_b32 v1, v16, v17 offset0:28 offset1:30
	v_lshl_add_u64 v[14:15], v[14:15], 2, s[50:51]
	s_waitcnt lgkmcnt(0)
	s_barrier
	global_load_dword v24, v[14:15], off
	ds_read2st64_b32 v[18:19], v35 offset0:32 offset1:64
	ds_read_b32 v25, v34
	ds_read_b32 v26, v35 offset:24576
	s_lshl_b64 s[6:7], s[6:7], 4
	v_lshl_add_u64 v[16:17], s[40:41], 2, v[6:7]
	v_lshl_add_u64 v[20:21], s[6:7], 0, v[2:3]
	s_waitcnt lgkmcnt(1)
	v_add_f32_e32 v18, v25, v18
	v_add_f32_e32 v18, v18, v19
	v_mad_u64_u32 v[22:23], s[0:1], v20, s15, v[16:17]
	s_waitcnt lgkmcnt(0)
	v_add_f32_e32 v18, v18, v26
	v_mad_i32_i24 v23, v21, s15, v23
	v_lshl_add_u64 v[20:21], s[6:7], 0, v[8:9]
	s_add_i32 s16, s16, s4
	v_readlane_b32 s48, v254, 28
	v_readlane_b32 s49, v254, 29
	s_cmpk_gt_i32 s16, 0x11f
	v_readlane_b32 s45, v254, 25
	v_readlane_b32 s46, v254, 26
	v_readlane_b32 s47, v254, 27
	v_readlane_b32 s52, v254, 32
	v_readlane_b32 s53, v254, 33
	v_readlane_b32 s54, v254, 34
	v_readlane_b32 s55, v254, 35
	v_readlane_b32 s56, v254, 36
	v_readlane_b32 s57, v254, 37
	v_readlane_b32 s58, v254, 38
	v_readlane_b32 s59, v254, 39
	s_waitcnt vmcnt(0)
	v_add_f32_e32 v18, v18, v24
	global_store_dword v[22:23], v18, off
	global_load_dword v24, v[14:15], off
	ds_read_b32 v25, v36
	ds_read_b32 v26, v37 offset:24576
	ds_read2st64_b32 v[18:19], v37 offset0:32 offset1:64
	v_mad_u64_u32 v[22:23], s[0:1], v20, s15, v[16:17]
	v_mad_i32_i24 v23, v21, s15, v23
	v_lshl_add_u64 v[20:21], s[6:7], 0, v[10:11]
	s_waitcnt lgkmcnt(0)
	v_add_f32_e32 v18, v25, v18
	v_add_f32_e32 v18, v18, v19
	v_add_f32_e32 v18, v18, v26
	s_waitcnt vmcnt(0)
	v_add_f32_e32 v18, v18, v24
	global_store_dword v[22:23], v18, off
	global_load_dword v24, v[14:15], off
	ds_read_b32 v25, v38
	ds_read_b32 v26, v39 offset:24576
	ds_read2st64_b32 v[18:19], v39 offset0:32 offset1:64
	v_mad_u64_u32 v[22:23], s[0:1], v20, s15, v[16:17]
	v_mad_i32_i24 v23, v21, s15, v23
	s_waitcnt lgkmcnt(0)
	v_add_f32_e32 v18, v25, v18
	v_add_f32_e32 v18, v18, v19
	v_add_f32_e32 v18, v18, v26
	s_waitcnt vmcnt(0)
	v_add_f32_e32 v18, v18, v24
	global_store_dword v[22:23], v18, off
	global_load_dword v20, v[14:15], off
	ds_read_b32 v21, v40
	ds_read_b32 v22, v41 offset:24576
	ds_read2st64_b32 v[14:15], v41 offset0:32 offset1:64
	v_lshl_add_u64 v[18:19], s[6:7], 0, v[12:13]
	v_mad_u64_u32 v[16:17], s[0:1], v18, s15, v[16:17]
	v_mad_i32_i24 v17, v19, s15, v17
	s_waitcnt lgkmcnt(0)
	v_add_f32_e32 v14, v21, v14
	v_add_f32_e32 v14, v14, v15
	v_add_f32_e32 v14, v14, v22
	s_waitcnt vmcnt(0)
	v_add_f32_e32 v14, v14, v20
	global_store_dword v[16:17], v14, off
	s_barrier
	s_cbranch_scc0 .LBB0_118

.LBB0_194:
	s_and_b32 s18, 0xffff, s17
	s_mov_b64 s[58:59], -1
	s_cmp_gt_i32 s18, 3
	s_mov_b64 s[6:7], -1
	s_cbranch_scc0 .LBB0_218
	v_mov_b32_e32 v137, v135
	v_and_b32_e32 v0, 0x100, v135
	v_lshrrev_b32_e32 v1, 1, v0
	v_lshrrev_b32_e32 v0, 2, v0
	v_or_b32_e32 v0, v0, v1
	v_xor_b32_e32 v137, v137, v0
	v_readlane_b32 s0, v252, 45
	s_mov_b32 s87, s64
	v_readlane_b32 s1, v252, 46
	v_ashrrev_i32_e32 v0, 6, v137
	v_readlane_b32 s62, v252, 2
	v_readlane_b32 s64, v252, 17
	v_readlane_b32 s66, v252, 47
	s_andn2_b64 vcc, exec, s[0:1]
	v_readfirstlane_b32 s0, v0
	v_readlane_b32 s63, v252, 3
	v_readlane_b32 s65, v252, 18
	v_readlane_b32 s67, v252, 48
	v_readlane_b32 s3, v252, 50
	s_mov_b32 s70, 0xc2fc0000
	s_movk_i32 s71, 0x1000
	s_mov_b32 s76, 0x20000
	s_mov_b32 s77, 0x40000
	s_mov_b32 s78, 0x60000
	s_mov_b32 s79, 0x80000
	s_mov_b32 s80, 0xa0000
	s_mov_b32 s81, 0xc0000
	s_mov_b32 s82, 0xe0000
	s_movk_i32 s83, 0x110
	s_cbranch_vccnz .LBB0_217
	s_mul_i32 s1, s16, 0x1600000
	s_add_u32 s19, s74, s1
	s_addc_u32 s20, s75, 0
	s_movk_i32 s1, 0x2100
	s_lshl_b32 s21, s0, 4
	v_cmp_gt_i32_e64 s[40:41], s1, v137
	s_ashr_i32 s1, s21, 31
	s_ashr_i32 s25, s0, 1
	v_lshlrev_b32_e32 v1, 3, v137
	v_lshlrev_b32_e32 v142, 3, v0
	v_lshrrev_b32_e32 v0, 1, v137
	s_cmp_gt_i32 s25, -1
	v_ashrrev_i32_e32 v132, 5, v137
	v_and_b32_e32 v2, 0xf8, v1
	v_lshlrev_b32_e32 v1, 1, v137
	v_mov_b32_e32 v145, s1
	v_and_b32_e32 v0, 24, v0
	s_cselect_b64 s[6:7], -1, 0
	s_lshl_b32 s1, s0, 6
	v_ashrrev_i32_e32 v133, 31, v132
	v_and_b32_e32 v140, 0x7e, v1
	v_ashrrev_i32_e32 v143, 31, v142
	v_and_or_b32 v144, v137, 15, s21
	s_lshl_b32 s22, s0, 5
	s_add_i32 s23, s1, 0
	v_add_u32_e32 v139, 0xfffffe00, v137
	v_lshl_add_u32 v141, v137, 2, s36
	s_add_i32 s25, s25, 1
	s_mov_b32 s34, 0
	v_lshlrev_b32_e32 v146, 1, v2
	v_lshlrev_b32_e32 v148, 1, v0
	s_mov_b32 s0, s2
	s_branch .LBB0_198

.LBB0_207:
	v_add_u32_e32 v205, 0, v201
	ds_read_b128 v[216:219], v205 offset:0
	ds_read_b128 v[220:223], v205 offset:8448
	ds_read_b128 v[224:227], v205 offset:64
	ds_read_b128 v[228:231], v205 offset:8512
	ds_read_b128 v[232:235], v205 offset:128
	ds_read_b128 v[236:239], v205 offset:8576
	ds_read_b128 v[240:243], v205 offset:192
	ds_read_b128 v[244:247], v205 offset:8640
	ds_read_b128 v[248:251], v205 offset:256
	ds_read_b128 v[128:131], v205 offset:8704
	v_cmp_ge_i32_e32 vcc, v34, v204
	v_or_b32_e32 v213, 3, v204
	v_or_b32_e32 v214, 2, v204
	v_or_b32_e32 v212, 16, v204
	v_or_b32_e32 v211, 17, v204
	s_add_i32 s55, s55, -1
	v_add_u32_e32 v201, 0x4200, v201
	s_cmp_eq_u32 s55, 0
	s_waitcnt vmcnt(11) lgkmcnt(9)
	v_mfma_f32_16x16x32_bf16 v[206:209], v[216:219], v[40:43], 0
	ds_read_b128 v[216:219], v205 offset:320
	s_waitcnt lgkmcnt(9)
	v_mfma_f32_16x16x32_bf16 v[124:127], v[220:223], v[40:43], 0
	ds_read_b128 v[220:223], v205 offset:8768
	s_waitcnt lgkmcnt(9)
	v_mfma_f32_16x16x32_bf16 v[206:209], v[224:227], v[24:27], v[206:209]
	ds_read_b128 v[224:227], v205 offset:384
	s_waitcnt lgkmcnt(9)
	v_mfma_f32_16x16x32_bf16 v[124:127], v[228:231], v[24:27], v[124:127]
	ds_read_b128 v[228:231], v205 offset:8832
	s_waitcnt lgkmcnt(9)
	v_mfma_f32_16x16x32_bf16 v[206:209], v[232:235], v[28:31], v[206:209]
	ds_read_b128 v[232:235], v205 offset:448
	s_waitcnt lgkmcnt(9)
	v_mfma_f32_16x16x32_bf16 v[124:127], v[236:239], v[28:31], v[124:127]
	ds_read_b128 v[236:239], v205 offset:8896
	s_waitcnt lgkmcnt(9)
	v_mfma_f32_16x16x32_bf16 v[206:209], v[240:243], v[36:39], v[206:209]
	s_waitcnt lgkmcnt(8)
	v_mfma_f32_16x16x32_bf16 v[124:127], v[244:247], v[36:39], v[124:127]
	s_waitcnt lgkmcnt(7)
	v_mfma_f32_16x16x32_bf16 v[206:209], v[248:251], v[44:47], v[206:209]
	s_waitcnt lgkmcnt(6)
	v_mfma_f32_16x16x32_bf16 v[124:127], v[128:131], v[44:47], v[124:127]
	s_waitcnt lgkmcnt(5)
	v_mfma_f32_16x16x32_bf16 v[206:209], v[216:219], v[52:55], v[206:209]
	s_waitcnt lgkmcnt(4)
	v_mfma_f32_16x16x32_bf16 v[124:127], v[220:223], v[52:55], v[124:127]
	s_waitcnt lgkmcnt(3)
	v_mfma_f32_16x16x32_bf16 v[206:209], v[224:227], v[56:59], v[206:209]
	s_waitcnt lgkmcnt(2)
	v_mfma_f32_16x16x32_bf16 v[124:127], v[228:231], v[56:59], v[124:127]
	s_waitcnt vmcnt(10) lgkmcnt(1)
	v_mfma_f32_16x16x32_bf16 v[206:209], v[232:235], v[60:63], v[206:209]
	s_waitcnt lgkmcnt(0)
	v_mfma_f32_16x16x32_bf16 v[124:127], v[236:239], v[60:63], v[124:127]
	s_nop 3
	v_cvt_f32_i32_e32 v129, v203
	v_add_u32_e32 v130, -1, v203
	v_cvt_f32_i32_e32 v130, v130
	v_mul_f32_e32 v128, 0x3d800000, v206
	v_mul_f32_e32 v129, v147, v129
	v_exp_f32_e32 v129, v129
	v_mul_f32_e32 v130, v147, v130
	v_exp_f32_e32 v130, v130
	v_pk_mul_f32 v[124:125], v[124:125], s[8:9] op_sel_hi:[1,0]
	v_mul_f32_e32 v128, v129, v128
	v_mul_f32_e32 v129, 0x3d800000, v207
	v_cndmask_b32_e32 v205, 0, v128, vcc
	v_cmp_gt_i32_e32 vcc, v34, v204
	v_mul_f32_e32 v129, v130, v129
	v_add_u32_e32 v128, -16, v203
	v_cndmask_b32_e32 v210, 0, v129, vcc
	v_subrev_u32_e32 v129, 17, v203
	v_cvt_f32_i32_e32 v128, v128
	v_cvt_f32_i32_e32 v129, v129
	v_pk_mul_f32 v[130:131], v[208:209], s[8:9] op_sel_hi:[1,0]
	v_pk_mul_f32 v[126:127], v[126:127], s[8:9] op_sel_hi:[1,0]
	v_mul_f32_e32 v128, v147, v128
	v_mul_f32_e32 v129, v147, v129
	v_exp_f32_e32 v128, v128
	v_exp_f32_e32 v129, v129
	v_cmp_ge_i32_e32 vcc, v34, v214
	v_or_b32_e32 v209, 18, v204
	v_or_b32_e32 v208, 19, v204
	v_pk_mul_f32 v[128:129], v[128:129], v[124:125]
	v_sub_u32_e32 v124, v34, v214
	v_sub_u32_e32 v125, v34, v213
	v_cvt_f32_i32_e32 v124, v124
	v_cvt_f32_i32_e32 v125, v125
	v_add_u32_e32 v204, 32, v204
	v_subrev_u32_e32 v203, 32, v203
	v_mul_f32_e32 v124, v147, v124
	v_mul_f32_e32 v125, v147, v125
	v_exp_f32_e32 v124, v124
	v_exp_f32_e32 v125, v125
	s_nop 0
	v_pk_mul_f32 v[130:131], v[124:125], v[130:131]
	v_sub_u32_e32 v124, v200, v214
	v_sub_u32_e32 v125, v200, v213
	v_cvt_f32_i32_e32 v124, v124
	v_cvt_f32_i32_e32 v125, v125
	v_mul_f32_e32 v124, v147, v124
	v_mul_f32_e32 v125, v147, v125
	v_exp_f32_e32 v124, v124
	v_exp_f32_e32 v125, v125
	s_nop 0
	v_pk_mul_f32 v[206:207], v[124:125], v[126:127]
	v_cvt_pk_bf16_f32 v125, v130, v131
	v_cndmask_b32_e32 v126, 0, v125, vcc
	v_lshrrev_b32_e32 v125, 16, v125
	v_cmp_ge_i32_e32 vcc, v35, v213
	v_cvt_pk_bf16_f32 v124, v205, v210
	v_add_u32_e32 v205, 0, v202
	v_add_u32_e32 v232, 0x1a100, v205
	ds_read_b64 v[216:217], v232
	ds_read_b64 v[218:219], v232 offset:32
	ds_read_b64 v[220:221], v232 offset:4352
	ds_read_b64 v[222:223], v232 offset:4384
	ds_read_b64 v[224:225], v232 offset:8704
	ds_read_b64 v[226:227], v232 offset:8736
	v_cndmask_b32_e32 v125, 0, v125, vcc
	v_perm_b32 v125, v125, v126, s13
	v_cvt_pk_bf16_f32 v126, v128, v129
	v_cmp_ge_i32_e32 vcc, v34, v212
	v_add_u32_e32 v130, 0x19020, v205
	ds_read_b64 v[130:131], v130
	v_cndmask_b32_e32 v127, 0, v126, vcc
	v_lshrrev_b32_e32 v126, 16, v126
	v_cmp_ge_i32_e32 vcc, v35, v211
	v_add_u32_e32 v202, 64, v202
	s_nop 0
	v_cndmask_b32_e32 v126, 0, v126, vcc
	v_perm_b32 v126, v126, v127, s13
	v_cvt_pk_bf16_f32 v127, v206, v207
	v_cmp_ge_i32_e32 vcc, v34, v209
	s_nop 1
	v_cndmask_b32_e32 v128, 0, v127, vcc
	v_lshrrev_b32_e32 v127, 16, v127
	v_cmp_ge_i32_e32 vcc, v35, v208
	s_nop 1
	v_cndmask_b32_e32 v127, 0, v127, vcc
	v_perm_b32 v127, v127, v128, s13
	v_add_u32_e32 v128, 0x19000, v205
	ds_read_b64 v[128:129], v128
	s_waitcnt lgkmcnt(0)
	v_mfma_f32_16x16x32_bf16 v[120:123], v[128:131], v[124:127], v[120:123]
	v_mfma_f32_16x16x32_bf16 v[116:119], v[216:219], v[124:127], v[116:119]
	v_mfma_f32_16x16x32_bf16 v[112:115], v[220:223], v[124:127], v[112:115]
	v_mfma_f32_16x16x32_bf16 v[108:111], v[224:227], v[124:127], v[108:111]
	s_cbranch_scc0 .LBB0_207
	s_mov_b64 s[60:61], 0

.LBB0_211:
	v_add_u32_e32 v35, 0, v195
	v_mad_u32_u24 v195, v164, s38, v35
	v_mad_i32_i24 v208, v167, s38, v35
	v_mad_i32_i24 v209, v166, s38, v35
	v_mad_i32_i24 v35, v165, s38, v35
	v_add_u32_e32 v195, 0x1d400, v195
	v_add_u32_e32 v208, 0x1d400, v208
	v_add_u32_e32 v209, 0x1d400, v209
	v_add_u32_e32 v35, 0x1d400, v35
	ds_read_b128 v[216:219], v195
	ds_read_b128 v[220:223], v208
	ds_read_b128 v[224:227], v209
	ds_read_b128 v[228:231], v35
	ds_read_b128 v[232:235], v195 offset:64
	ds_read_b128 v[236:239], v208 offset:64
	ds_read_b128 v[240:243], v209 offset:64
	ds_read_b128 v[244:247], v35 offset:64
	ds_read_b128 v[248:251], v195 offset:128
	ds_read_b128 v[204:207], v208 offset:128
	v_xor_b32_e32 v212, 0x80, v194
	v_cmp_gt_u32_e32 vcc, 16, v151
	s_waitcnt vmcnt(11) lgkmcnt(9)
	v_mfma_f32_16x16x32_bf16 v[124:127], v[216:219], v[40:43], 0
	ds_read_b128 v[216:219], v209 offset:128
	s_waitcnt lgkmcnt(9)
	v_mfma_f32_16x16x32_bf16 v[128:131], v[220:223], v[40:43], 0
	ds_read_b128 v[220:223], v35 offset:128
	s_waitcnt lgkmcnt(9)
	v_mfma_f32_16x16x32_bf16 v[196:199], v[224:227], v[40:43], 0
	ds_read_b128 v[224:227], v195 offset:192
	s_waitcnt lgkmcnt(9)
	v_mfma_f32_16x16x32_bf16 v[200:203], v[228:231], v[40:43], 0
	ds_read_b128 v[228:231], v208 offset:192
	s_waitcnt lgkmcnt(9)
	v_mfma_f32_16x16x32_bf16 v[124:127], v[232:235], v[24:27], v[124:127]
	ds_read_b128 v[232:235], v209 offset:192
	s_waitcnt lgkmcnt(9)
	v_mfma_f32_16x16x32_bf16 v[128:131], v[236:239], v[24:27], v[128:131]
	ds_read_b128 v[236:239], v35 offset:192
	s_waitcnt lgkmcnt(9)
	v_mfma_f32_16x16x32_bf16 v[196:199], v[240:243], v[24:27], v[196:199]
	ds_read_b128 v[240:243], v195 offset:256
	s_waitcnt lgkmcnt(9)
	v_mfma_f32_16x16x32_bf16 v[200:203], v[244:247], v[24:27], v[200:203]
	ds_read_b128 v[244:247], v208 offset:256
	s_waitcnt lgkmcnt(9)
	v_mfma_f32_16x16x32_bf16 v[124:127], v[248:251], v[28:31], v[124:127]
	ds_read_b128 v[248:251], v209 offset:256
	s_waitcnt lgkmcnt(9)
	v_mfma_f32_16x16x32_bf16 v[128:131], v[204:207], v[28:31], v[128:131]
	ds_read_b128 v[204:207], v35 offset:256
	s_waitcnt lgkmcnt(9)
	v_mfma_f32_16x16x32_bf16 v[196:199], v[216:219], v[28:31], v[196:199]
	ds_read_b128 v[216:219], v195 offset:320
	s_waitcnt lgkmcnt(9)
	v_mfma_f32_16x16x32_bf16 v[200:203], v[220:223], v[28:31], v[200:203]
	ds_read_b128 v[220:223], v208 offset:320
	s_waitcnt lgkmcnt(9)
	v_mfma_f32_16x16x32_bf16 v[124:127], v[224:227], v[36:39], v[124:127]
	ds_read_b128 v[224:227], v209 offset:320
	s_waitcnt lgkmcnt(9)
	v_mfma_f32_16x16x32_bf16 v[128:131], v[228:231], v[36:39], v[128:131]
	ds_read_b128 v[228:231], v35 offset:320
	s_waitcnt lgkmcnt(9)
	v_mfma_f32_16x16x32_bf16 v[196:199], v[232:235], v[36:39], v[196:199]
	ds_read_b128 v[232:235], v195 offset:384
	s_waitcnt lgkmcnt(9)
	v_mfma_f32_16x16x32_bf16 v[200:203], v[236:239], v[36:39], v[200:203]
	ds_read_b128 v[236:239], v208 offset:384
	s_waitcnt lgkmcnt(9)
	v_mfma_f32_16x16x32_bf16 v[124:127], v[240:243], v[44:47], v[124:127]
	ds_read_b128 v[240:243], v209 offset:384
	s_waitcnt lgkmcnt(9)
	v_mfma_f32_16x16x32_bf16 v[128:131], v[244:247], v[44:47], v[128:131]
	ds_read_b128 v[244:247], v35 offset:384
	s_waitcnt lgkmcnt(9)
	v_mfma_f32_16x16x32_bf16 v[196:199], v[248:251], v[44:47], v[196:199]
	ds_read_b128 v[248:251], v195 offset:448
	s_waitcnt lgkmcnt(9)
	v_mfma_f32_16x16x32_bf16 v[200:203], v[204:207], v[44:47], v[200:203]
	ds_read_b128 v[204:207], v208 offset:448
	s_waitcnt lgkmcnt(9)
	v_mfma_f32_16x16x32_bf16 v[124:127], v[216:219], v[52:55], v[124:127]
	ds_read_b128 v[216:219], v209 offset:448
	s_waitcnt lgkmcnt(9)
	v_mfma_f32_16x16x32_bf16 v[128:131], v[220:223], v[52:55], v[128:131]
	ds_read_b128 v[220:223], v35 offset:448
	s_waitcnt lgkmcnt(9)
	v_mfma_f32_16x16x32_bf16 v[196:199], v[224:227], v[52:55], v[196:199]
	s_waitcnt lgkmcnt(8)
	v_mfma_f32_16x16x32_bf16 v[200:203], v[228:231], v[52:55], v[200:203]
	s_waitcnt lgkmcnt(7)
	v_mfma_f32_16x16x32_bf16 v[124:127], v[232:235], v[56:59], v[124:127]
	s_waitcnt lgkmcnt(6)
	v_mfma_f32_16x16x32_bf16 v[128:131], v[236:239], v[56:59], v[128:131]
	s_waitcnt lgkmcnt(5)
	v_mfma_f32_16x16x32_bf16 v[196:199], v[240:243], v[56:59], v[196:199]
	s_waitcnt lgkmcnt(4)
	v_mfma_f32_16x16x32_bf16 v[200:203], v[244:247], v[56:59], v[200:203]
	s_waitcnt vmcnt(10) lgkmcnt(3)
	v_mfma_f32_16x16x32_bf16 v[124:127], v[248:251], v[60:63], v[124:127]
	s_waitcnt lgkmcnt(2)
	v_mfma_f32_16x16x32_bf16 v[128:131], v[204:207], v[60:63], v[128:131]
	s_waitcnt lgkmcnt(1)
	v_mfma_f32_16x16x32_bf16 v[196:199], v[216:219], v[60:63], v[196:199]
	s_waitcnt lgkmcnt(0)
	v_mfma_f32_16x16x32_bf16 v[200:203], v[220:223], v[60:63], v[200:203]
	v_add_u32_e32 v35, 1, v34
	v_cvt_f32_i32_e32 v35, v35
	v_mul_f32_e32 v35, v147, v35
	v_exp_f32_e32 v204, v35
	v_ashrrev_i32_e32 v35, 31, v34
	v_lshl_add_u64 v[34:35], s[42:43], 0, v[34:35]
	v_lshlrev_b64 v[206:207], 12, v[34:35]
	v_pk_fma_f32 v[122:123], v[204:205], v[126:127], v[122:123] op_sel_hi:[0,1,1]
	v_lshl_add_u64 v[206:207], s[46:47], 0, v[206:207]
	v_pk_fma_f32 v[120:121], v[204:205], v[124:125], v[120:121] op_sel_hi:[0,1,1]
	v_mul_f32_e32 v205, v122, v122
	v_lshl_add_u64 v[206:207], v[32:33], 1, v[206:207]
	v_cvt_pk_bf16_f32 v124, v120, v121
	v_cvt_pk_bf16_f32 v125, v122, v123
	v_pk_fma_f32 v[118:119], v[204:205], v[130:131], v[118:119] op_sel_hi:[0,1,1]
	v_pk_fma_f32 v[116:117], v[204:205], v[128:129], v[116:117] op_sel_hi:[0,1,1]
	global_store_dwordx2 v[206:207], v[124:125], off
	v_add_f32_e32 v124, v120, v121
	v_mul_f32_e32 v195, v120, v120
	v_mul_f32_e32 v121, v121, v121
	v_cvt_pk_bf16_f32 v128, v116, v117
	v_cvt_pk_bf16_f32 v129, v118, v119
	v_mul_f32_e32 v120, v118, v118
	v_add_f32_e32 v126, v122, v123
	v_mul_f32_e32 v123, v123, v123
	global_store_dwordx2 v[206:207], v[128:129], off offset:32
	v_pk_fma_f32 v[128:129], v[118:119], v[118:119], v[120:121] op_sel_hi:[1,1,0]
	v_pk_fma_f32 v[114:115], v[204:205], v[198:199], v[114:115] op_sel_hi:[0,1,1]
	v_pk_fma_f32 v[112:113], v[204:205], v[196:197], v[112:113] op_sel_hi:[0,1,1]
	v_pk_fma_f32 v[110:111], v[204:205], v[202:203], v[110:111] op_sel_hi:[0,1,1]
	v_pk_fma_f32 v[108:109], v[204:205], v[200:201], v[108:109] op_sel_hi:[0,1,1]
	v_mov_b32_e32 v194, v116
	v_mov_b32_e32 v120, v117
	v_mov_b32_e32 v204, v118
	v_mov_b32_e32 v122, v119
	v_mul_f32_e32 v125, v116, v116
	v_mul_f32_e32 v127, v117, v117
	v_cvt_pk_bf16_f32 v130, v112, v113
	v_cvt_pk_bf16_f32 v131, v114, v115
	v_pk_add_f32 v[116:117], v[194:195], v[120:121]
	v_pk_add_f32 v[118:119], v[204:205], v[122:123]
	global_store_dwordx2 v[206:207], v[130:131], off offset:64
	v_mul_f32_e32 v131, v112, v112
	v_mul_f32_e32 v197, v113, v113
	v_mul_f32_e32 v199, v114, v114
	v_mul_f32_e32 v209, v115, v115
	v_cvt_pk_bf16_f32 v200, v108, v109
	v_cvt_pk_bf16_f32 v201, v110, v111
	v_pk_add_f32 v[116:117], v[116:117], v[118:119]
	v_pk_add_f32 v[118:119], v[124:125], v[126:127]
	v_mov_b32_e32 v128, v33
	v_mov_b32_e32 v130, v112
	v_mov_b32_e32 v196, v113
	v_mov_b32_e32 v198, v114
	v_mov_b32_e32 v208, v115
	global_store_dwordx2 v[206:207], v[200:201], off offset:96
	v_mul_f32_e32 v201, v108, v108
	v_mul_f32_e32 v203, v109, v109
	v_mul_f32_e32 v207, v110, v110
	v_mul_f32_e32 v211, v111, v111
	v_pk_add_f32 v[118:119], v[118:119], v[128:129]
	v_pk_add_f32 v[112:113], v[130:131], v[196:197]
	v_pk_add_f32 v[114:115], v[198:199], v[208:209]
	v_mov_b32_e32 v200, v108
	v_mov_b32_e32 v202, v109
	v_mov_b32_e32 v206, v110
	v_mov_b32_e32 v210, v111
	v_pk_add_f32 v[116:117], v[116:117], v[118:119]
	v_pk_add_f32 v[112:113], v[112:113], v[114:115]
	v_pk_add_f32 v[108:109], v[200:201], v[202:203]
	v_pk_add_f32 v[110:111], v[206:207], v[210:211]
	v_pk_add_f32 v[112:113], v[116:117], v[112:113]
	v_pk_add_f32 v[108:109], v[108:109], v[110:111]
	s_nop 0
	v_pk_add_f32 v[108:109], v[112:113], v[108:109]
	ds_swizzle_b32 v110, v108 offset:swizzle(SWAP,16)
	ds_swizzle_b32 v111, v109 offset:swizzle(SWAP,16)
	s_waitcnt lgkmcnt(0)
	v_pk_add_f32 v[108:109], v[108:109], v[110:111]
	ds_bpermute_b32 v110, v212, v108
	ds_bpermute_b32 v111, v212, v109
	s_and_saveexec_b64 s[42:43], vcc
	s_cbranch_execz .LBB0_213
	v_lshlrev_b64 v[112:113], 8, v[34:35]
	v_lshl_add_u64 v[112:113], s[50:51], 0, v[112:113]
	s_waitcnt lgkmcnt(0)
	v_pk_add_f32 v[108:109], v[108:109], v[110:111]
	global_store_dwordx2 v[112:113], v[108:109], off
